# sw_item (shift@W partials) loop software-pipelined, 32 loads in flight
# speedup vs baseline: 1.0519x; 1.0099x over previous
.LBB0_107:
	global_load_dword v6, v[0:1], off
	v_add_u32_e32 v4, 0x100, v4
	v_cmp_lt_u32_e32 vcc, 63, v4
	v_lshl_add_u64 v[0:1], v[0:1], 0, s[4:5]
	s_or_b64 s[8:9], vcc, s[8:9]
	s_waitcnt vmcnt(0)
	ds_write_b32 v5, v6
	v_add_u32_e32 v5, 0x400, v5
	s_andn2_b64 exec, exec, s[8:9]
	s_cbranch_execnz .LBB0_107
	s_or_b64 exec, exec, s[8:9]
	s_mul_i32 s26, s26, 5
	s_sub_i32 s7, s7, s26
	s_sext_i32_i8 s7, s7
	v_lshl_add_u32 v0, s7, 1, v3
	v_cmp_gt_i32_e32 vcc, 9, v0
	s_waitcnt lgkmcnt(0)
	s_barrier
	s_and_saveexec_b64 s[8:9], vcc
	s_cbranch_execz .LBB0_105
	s_ashr_i32 s7, s6, 31
	s_lshl_b64 s[26:27], s[6:7], 10
	s_add_u32 s7, s26, s10
	s_addc_u32 s10, s27, s11
	s_mulk_i32 s10, 0x2400
	s_mul_hi_u32 s11, s7, 0x2400
	v_readlane_b32 s36, v254, 0
	s_add_i32 s11, s11, s10
	s_mulk_i32 s7, 0x2400
	v_readlane_b32 s38, v254, 2
	v_lshl_or_b32 v0, v0, 8, v2
	v_readlane_b32 s39, v254, 3
	s_add_u32 s10, s38, s7
	s_addc_u32 s11, s39, s11
	v_ashrrev_i32_e32 v1, 31, v0
	v_mov_b32_e32 v9, 0
	v_lshl_add_u64 v[4:5], v[0:1], 2, s[10:11]
	s_mov_b64 s[10:11], 0
	v_mov_b32_e32 v6, 0
	v_mov_b32_e32 v7, v9
	v_mov_b32_e32 v2, 0
	v_mov_b32_e32 v3, v9
	v_readlane_b32 s37, v254, 1
	v_readlane_b32 s40, v254, 4
	v_readlane_b32 s41, v254, 5
	v_readlane_b32 s42, v254, 6
	v_readlane_b32 s43, v254, 7
	v_readlane_b32 s44, v254, 8
	v_readlane_b32 s45, v254, 9
	v_readlane_b32 s46, v254, 10
	v_readlane_b32 s47, v254, 11
	v_readlane_b32 s48, v254, 12
	v_readlane_b32 s49, v254, 13
	v_readlane_b32 s50, v254, 14
	v_readlane_b32 s51, v254, 15
	s_mov_b64 s[10:11], 0x2400
	v_mov_b64_e32 v[200:201], v[4:5]
	v_lshl_add_u64 v[202:203], v[200:201], 0, s[10:11]
	v_lshl_add_u64 v[204:205], v[202:203], 0, s[10:11]
	v_lshl_add_u64 v[206:207], v[204:205], 0, s[10:11]
	v_lshl_add_u64 v[208:209], v[206:207], 0, s[10:11]
	v_lshl_add_u64 v[210:211], v[208:209], 0, s[10:11]
	v_lshl_add_u64 v[212:213], v[210:211], 0, s[10:11]
	v_lshl_add_u64 v[214:215], v[212:213], 0, s[10:11]
	s_mov_b64 s[10:11], 0x12000
	global_load_dword v216, v[200:201], off nt
	global_load_dword v217, v[202:203], off nt
	global_load_dword v218, v[204:205], off nt
	global_load_dword v219, v[206:207], off nt
	global_load_dword v220, v[208:209], off nt
	global_load_dword v221, v[210:211], off nt
	global_load_dword v222, v[212:213], off nt
	global_load_dword v223, v[214:215], off nt
	v_lshl_add_u64 v[200:201], v[200:201], 0, s[10:11]
	v_lshl_add_u64 v[202:203], v[202:203], 0, s[10:11]
	v_lshl_add_u64 v[204:205], v[204:205], 0, s[10:11]
	v_lshl_add_u64 v[206:207], v[206:207], 0, s[10:11]
	v_lshl_add_u64 v[208:209], v[208:209], 0, s[10:11]
	v_lshl_add_u64 v[210:211], v[210:211], 0, s[10:11]
	v_lshl_add_u64 v[212:213], v[212:213], 0, s[10:11]
	v_lshl_add_u64 v[214:215], v[214:215], 0, s[10:11]
	global_load_dword v224, v[200:201], off nt
	global_load_dword v225, v[202:203], off nt
	global_load_dword v226, v[204:205], off nt
	global_load_dword v227, v[206:207], off nt
	global_load_dword v228, v[208:209], off nt
	global_load_dword v229, v[210:211], off nt
	global_load_dword v230, v[212:213], off nt
	global_load_dword v231, v[214:215], off nt
	v_lshl_add_u64 v[200:201], v[200:201], 0, s[10:11]
	v_lshl_add_u64 v[202:203], v[202:203], 0, s[10:11]
	v_lshl_add_u64 v[204:205], v[204:205], 0, s[10:11]
	v_lshl_add_u64 v[206:207], v[206:207], 0, s[10:11]
	v_lshl_add_u64 v[208:209], v[208:209], 0, s[10:11]
	v_lshl_add_u64 v[210:211], v[210:211], 0, s[10:11]
	v_lshl_add_u64 v[212:213], v[212:213], 0, s[10:11]
	v_lshl_add_u64 v[214:215], v[214:215], 0, s[10:11]
	global_load_dword v240, v[200:201], off nt
	global_load_dword v241, v[202:203], off nt
	global_load_dword v242, v[204:205], off nt
	global_load_dword v243, v[206:207], off nt
	global_load_dword v244, v[208:209], off nt
	global_load_dword v245, v[210:211], off nt
	global_load_dword v246, v[212:213], off nt
	global_load_dword v247, v[214:215], off nt
	v_lshl_add_u64 v[200:201], v[200:201], 0, s[10:11]
	v_lshl_add_u64 v[202:203], v[202:203], 0, s[10:11]
	v_lshl_add_u64 v[204:205], v[204:205], 0, s[10:11]
	v_lshl_add_u64 v[206:207], v[206:207], 0, s[10:11]
	v_lshl_add_u64 v[208:209], v[208:209], 0, s[10:11]
	v_lshl_add_u64 v[210:211], v[210:211], 0, s[10:11]
	v_lshl_add_u64 v[212:213], v[212:213], 0, s[10:11]
	v_lshl_add_u64 v[214:215], v[214:215], 0, s[10:11]
	global_load_dword v232, v[200:201], off nt
	global_load_dword v233, v[202:203], off nt
	global_load_dword v234, v[204:205], off nt
	global_load_dword v235, v[206:207], off nt
	global_load_dword v236, v[208:209], off nt
	global_load_dword v237, v[210:211], off nt
	global_load_dword v238, v[212:213], off nt
	global_load_dword v248, v[214:215], off nt
	v_lshl_add_u64 v[200:201], v[200:201], 0, s[10:11]
	v_lshl_add_u64 v[202:203], v[202:203], 0, s[10:11]
	v_lshl_add_u64 v[204:205], v[204:205], 0, s[10:11]
	v_lshl_add_u64 v[206:207], v[206:207], 0, s[10:11]
	v_lshl_add_u64 v[208:209], v[208:209], 0, s[10:11]
	v_lshl_add_u64 v[210:211], v[210:211], 0, s[10:11]
	v_lshl_add_u64 v[212:213], v[212:213], 0, s[10:11]
	v_lshl_add_u64 v[214:215], v[214:215], 0, s[10:11]
	ds_read_b128 v[10:13], v8
	ds_read_b128 v[14:17], v8 offset:16
	ds_read_b128 v[18:21], v8 offset:256
	ds_read_b128 v[22:25], v8 offset:272
	ds_read_b128 v[26:29], v8 offset:512
	ds_read_b128 v[30:33], v8 offset:528
	ds_read_b128 v[34:37], v8 offset:768
	ds_read_b128 v[38:41], v8 offset:784
	ds_read_b128 v[42:45], v8 offset:1024
	ds_read_b128 v[46:49], v8 offset:1040
	v_add_u32_e32 v8, 32, v8
	s_waitcnt vmcnt(24) lgkmcnt(0)
	v_fmac_f32_e32 v6, v216, v10
	v_fmac_f32_e32 v7, v216, v18
	v_fmac_f32_e32 v9, v216, v26
	v_fmac_f32_e32 v3, v216, v34
	v_fmac_f32_e32 v2, v216, v42
	v_fmac_f32_e32 v6, v217, v11
	v_fmac_f32_e32 v7, v217, v19
	v_fmac_f32_e32 v9, v217, v27
	v_fmac_f32_e32 v3, v217, v35
	v_fmac_f32_e32 v2, v217, v43
	v_fmac_f32_e32 v6, v218, v12
	v_fmac_f32_e32 v7, v218, v20
	v_fmac_f32_e32 v9, v218, v28
	v_fmac_f32_e32 v3, v218, v36
	v_fmac_f32_e32 v2, v218, v44
	v_fmac_f32_e32 v6, v219, v13
	v_fmac_f32_e32 v7, v219, v21
	v_fmac_f32_e32 v9, v219, v29
	v_fmac_f32_e32 v3, v219, v37
	v_fmac_f32_e32 v2, v219, v45
	v_fmac_f32_e32 v6, v220, v14
	v_fmac_f32_e32 v7, v220, v22
	v_fmac_f32_e32 v9, v220, v30
	v_fmac_f32_e32 v3, v220, v38
	v_fmac_f32_e32 v2, v220, v46
	v_fmac_f32_e32 v6, v221, v15
	v_fmac_f32_e32 v7, v221, v23
	v_fmac_f32_e32 v9, v221, v31
	v_fmac_f32_e32 v3, v221, v39
	v_fmac_f32_e32 v2, v221, v47
	v_fmac_f32_e32 v6, v222, v16
	v_fmac_f32_e32 v7, v222, v24
	v_fmac_f32_e32 v9, v222, v32
	v_fmac_f32_e32 v3, v222, v40
	v_fmac_f32_e32 v2, v222, v48
	v_fmac_f32_e32 v6, v223, v17
	v_fmac_f32_e32 v7, v223, v25
	v_fmac_f32_e32 v9, v223, v33
	v_fmac_f32_e32 v3, v223, v41
	v_fmac_f32_e32 v2, v223, v49
	global_load_dword v216, v[200:201], off nt
	global_load_dword v217, v[202:203], off nt
	global_load_dword v218, v[204:205], off nt
	global_load_dword v219, v[206:207], off nt
	global_load_dword v220, v[208:209], off nt
	global_load_dword v221, v[210:211], off nt
	global_load_dword v222, v[212:213], off nt
	global_load_dword v223, v[214:215], off nt
	v_lshl_add_u64 v[200:201], v[200:201], 0, s[10:11]
	v_lshl_add_u64 v[202:203], v[202:203], 0, s[10:11]
	v_lshl_add_u64 v[204:205], v[204:205], 0, s[10:11]
	v_lshl_add_u64 v[206:207], v[206:207], 0, s[10:11]
	v_lshl_add_u64 v[208:209], v[208:209], 0, s[10:11]
	v_lshl_add_u64 v[210:211], v[210:211], 0, s[10:11]
	v_lshl_add_u64 v[212:213], v[212:213], 0, s[10:11]
	v_lshl_add_u64 v[214:215], v[214:215], 0, s[10:11]
	ds_read_b128 v[10:13], v8
	ds_read_b128 v[14:17], v8 offset:16
	ds_read_b128 v[18:21], v8 offset:256
	ds_read_b128 v[22:25], v8 offset:272
	ds_read_b128 v[26:29], v8 offset:512
	ds_read_b128 v[30:33], v8 offset:528
	ds_read_b128 v[34:37], v8 offset:768
	ds_read_b128 v[38:41], v8 offset:784
	ds_read_b128 v[42:45], v8 offset:1024
	ds_read_b128 v[46:49], v8 offset:1040
	v_add_u32_e32 v8, 32, v8
	s_waitcnt vmcnt(24) lgkmcnt(0)
	v_fmac_f32_e32 v6, v224, v10
	v_fmac_f32_e32 v7, v224, v18
	v_fmac_f32_e32 v9, v224, v26
	v_fmac_f32_e32 v3, v224, v34
	v_fmac_f32_e32 v2, v224, v42
	v_fmac_f32_e32 v6, v225, v11
	v_fmac_f32_e32 v7, v225, v19
	v_fmac_f32_e32 v9, v225, v27
	v_fmac_f32_e32 v3, v225, v35
	v_fmac_f32_e32 v2, v225, v43
	v_fmac_f32_e32 v6, v226, v12
	v_fmac_f32_e32 v7, v226, v20
	v_fmac_f32_e32 v9, v226, v28
	v_fmac_f32_e32 v3, v226, v36
	v_fmac_f32_e32 v2, v226, v44
	v_fmac_f32_e32 v6, v227, v13
	v_fmac_f32_e32 v7, v227, v21
	v_fmac_f32_e32 v9, v227, v29
	v_fmac_f32_e32 v3, v227, v37
	v_fmac_f32_e32 v2, v227, v45
	v_fmac_f32_e32 v6, v228, v14
	v_fmac_f32_e32 v7, v228, v22
	v_fmac_f32_e32 v9, v228, v30
	v_fmac_f32_e32 v3, v228, v38
	v_fmac_f32_e32 v2, v228, v46
	v_fmac_f32_e32 v6, v229, v15
	v_fmac_f32_e32 v7, v229, v23
	v_fmac_f32_e32 v9, v229, v31
	v_fmac_f32_e32 v3, v229, v39
	v_fmac_f32_e32 v2, v229, v47
	v_fmac_f32_e32 v6, v230, v16
	v_fmac_f32_e32 v7, v230, v24
	v_fmac_f32_e32 v9, v230, v32
	v_fmac_f32_e32 v3, v230, v40
	v_fmac_f32_e32 v2, v230, v48
	v_fmac_f32_e32 v6, v231, v17
	v_fmac_f32_e32 v7, v231, v25
	v_fmac_f32_e32 v9, v231, v33
	v_fmac_f32_e32 v3, v231, v41
	v_fmac_f32_e32 v2, v231, v49
	global_load_dword v224, v[200:201], off nt
	global_load_dword v225, v[202:203], off nt
	global_load_dword v226, v[204:205], off nt
	global_load_dword v227, v[206:207], off nt
	global_load_dword v228, v[208:209], off nt
	global_load_dword v229, v[210:211], off nt
	global_load_dword v230, v[212:213], off nt
	global_load_dword v231, v[214:215], off nt
	v_lshl_add_u64 v[200:201], v[200:201], 0, s[10:11]
	v_lshl_add_u64 v[202:203], v[202:203], 0, s[10:11]
	v_lshl_add_u64 v[204:205], v[204:205], 0, s[10:11]
	v_lshl_add_u64 v[206:207], v[206:207], 0, s[10:11]
	v_lshl_add_u64 v[208:209], v[208:209], 0, s[10:11]
	v_lshl_add_u64 v[210:211], v[210:211], 0, s[10:11]
	v_lshl_add_u64 v[212:213], v[212:213], 0, s[10:11]
	v_lshl_add_u64 v[214:215], v[214:215], 0, s[10:11]
	ds_read_b128 v[10:13], v8
	ds_read_b128 v[14:17], v8 offset:16
	ds_read_b128 v[18:21], v8 offset:256
	ds_read_b128 v[22:25], v8 offset:272
	ds_read_b128 v[26:29], v8 offset:512
	ds_read_b128 v[30:33], v8 offset:528
	ds_read_b128 v[34:37], v8 offset:768
	ds_read_b128 v[38:41], v8 offset:784
	ds_read_b128 v[42:45], v8 offset:1024
	ds_read_b128 v[46:49], v8 offset:1040
	v_add_u32_e32 v8, 32, v8
	s_waitcnt vmcnt(24) lgkmcnt(0)
	v_fmac_f32_e32 v6, v240, v10
	v_fmac_f32_e32 v7, v240, v18
	v_fmac_f32_e32 v9, v240, v26
	v_fmac_f32_e32 v3, v240, v34
	v_fmac_f32_e32 v2, v240, v42
	v_fmac_f32_e32 v6, v241, v11
	v_fmac_f32_e32 v7, v241, v19
	v_fmac_f32_e32 v9, v241, v27
	v_fmac_f32_e32 v3, v241, v35
	v_fmac_f32_e32 v2, v241, v43
	v_fmac_f32_e32 v6, v242, v12
	v_fmac_f32_e32 v7, v242, v20
	v_fmac_f32_e32 v9, v242, v28
	v_fmac_f32_e32 v3, v242, v36
	v_fmac_f32_e32 v2, v242, v44
	v_fmac_f32_e32 v6, v243, v13
	v_fmac_f32_e32 v7, v243, v21
	v_fmac_f32_e32 v9, v243, v29
	v_fmac_f32_e32 v3, v243, v37
	v_fmac_f32_e32 v2, v243, v45
	v_fmac_f32_e32 v6, v244, v14
	v_fmac_f32_e32 v7, v244, v22
	v_fmac_f32_e32 v9, v244, v30
	v_fmac_f32_e32 v3, v244, v38
	v_fmac_f32_e32 v2, v244, v46
	v_fmac_f32_e32 v6, v245, v15
	v_fmac_f32_e32 v7, v245, v23
	v_fmac_f32_e32 v9, v245, v31
	v_fmac_f32_e32 v3, v245, v39
	v_fmac_f32_e32 v2, v245, v47
	v_fmac_f32_e32 v6, v246, v16
	v_fmac_f32_e32 v7, v246, v24
	v_fmac_f32_e32 v9, v246, v32
	v_fmac_f32_e32 v3, v246, v40
	v_fmac_f32_e32 v2, v246, v48
	v_fmac_f32_e32 v6, v247, v17
	v_fmac_f32_e32 v7, v247, v25
	v_fmac_f32_e32 v9, v247, v33
	v_fmac_f32_e32 v3, v247, v41
	v_fmac_f32_e32 v2, v247, v49
	global_load_dword v240, v[200:201], off nt
	global_load_dword v241, v[202:203], off nt
	global_load_dword v242, v[204:205], off nt
	global_load_dword v243, v[206:207], off nt
	global_load_dword v244, v[208:209], off nt
	global_load_dword v245, v[210:211], off nt
	global_load_dword v246, v[212:213], off nt
	global_load_dword v247, v[214:215], off nt
	v_lshl_add_u64 v[200:201], v[200:201], 0, s[10:11]
	v_lshl_add_u64 v[202:203], v[202:203], 0, s[10:11]
	v_lshl_add_u64 v[204:205], v[204:205], 0, s[10:11]
	v_lshl_add_u64 v[206:207], v[206:207], 0, s[10:11]
	v_lshl_add_u64 v[208:209], v[208:209], 0, s[10:11]
	v_lshl_add_u64 v[210:211], v[210:211], 0, s[10:11]
	v_lshl_add_u64 v[212:213], v[212:213], 0, s[10:11]
	v_lshl_add_u64 v[214:215], v[214:215], 0, s[10:11]
	ds_read_b128 v[10:13], v8
	ds_read_b128 v[14:17], v8 offset:16
	ds_read_b128 v[18:21], v8 offset:256
	ds_read_b128 v[22:25], v8 offset:272
	ds_read_b128 v[26:29], v8 offset:512
	ds_read_b128 v[30:33], v8 offset:528
	ds_read_b128 v[34:37], v8 offset:768
	ds_read_b128 v[38:41], v8 offset:784
	ds_read_b128 v[42:45], v8 offset:1024
	ds_read_b128 v[46:49], v8 offset:1040
	v_add_u32_e32 v8, 32, v8
	s_waitcnt vmcnt(24) lgkmcnt(0)
	v_fmac_f32_e32 v6, v232, v10
	v_fmac_f32_e32 v7, v232, v18
	v_fmac_f32_e32 v9, v232, v26
	v_fmac_f32_e32 v3, v232, v34
	v_fmac_f32_e32 v2, v232, v42
	v_fmac_f32_e32 v6, v233, v11
	v_fmac_f32_e32 v7, v233, v19
	v_fmac_f32_e32 v9, v233, v27
	v_fmac_f32_e32 v3, v233, v35
	v_fmac_f32_e32 v2, v233, v43
	v_fmac_f32_e32 v6, v234, v12
	v_fmac_f32_e32 v7, v234, v20
	v_fmac_f32_e32 v9, v234, v28
	v_fmac_f32_e32 v3, v234, v36
	v_fmac_f32_e32 v2, v234, v44
	v_fmac_f32_e32 v6, v235, v13
	v_fmac_f32_e32 v7, v235, v21
	v_fmac_f32_e32 v9, v235, v29
	v_fmac_f32_e32 v3, v235, v37
	v_fmac_f32_e32 v2, v235, v45
	v_fmac_f32_e32 v6, v236, v14
	v_fmac_f32_e32 v7, v236, v22
	v_fmac_f32_e32 v9, v236, v30
	v_fmac_f32_e32 v3, v236, v38
	v_fmac_f32_e32 v2, v236, v46
	v_fmac_f32_e32 v6, v237, v15
	v_fmac_f32_e32 v7, v237, v23
	v_fmac_f32_e32 v9, v237, v31
	v_fmac_f32_e32 v3, v237, v39
	v_fmac_f32_e32 v2, v237, v47
	v_fmac_f32_e32 v6, v238, v16
	v_fmac_f32_e32 v7, v238, v24
	v_fmac_f32_e32 v9, v238, v32
	v_fmac_f32_e32 v3, v238, v40
	v_fmac_f32_e32 v2, v238, v48
	v_fmac_f32_e32 v6, v248, v17
	v_fmac_f32_e32 v7, v248, v25
	v_fmac_f32_e32 v9, v248, v33
	v_fmac_f32_e32 v3, v248, v41
	v_fmac_f32_e32 v2, v248, v49
	global_load_dword v232, v[200:201], off nt
	global_load_dword v233, v[202:203], off nt
	global_load_dword v234, v[204:205], off nt
	global_load_dword v235, v[206:207], off nt
	global_load_dword v236, v[208:209], off nt
	global_load_dword v237, v[210:211], off nt
	global_load_dword v238, v[212:213], off nt
	global_load_dword v248, v[214:215], off nt
	v_lshl_add_u64 v[200:201], v[200:201], 0, s[10:11]
	v_lshl_add_u64 v[202:203], v[202:203], 0, s[10:11]
	v_lshl_add_u64 v[204:205], v[204:205], 0, s[10:11]
	v_lshl_add_u64 v[206:207], v[206:207], 0, s[10:11]
	v_lshl_add_u64 v[208:209], v[208:209], 0, s[10:11]
	v_lshl_add_u64 v[210:211], v[210:211], 0, s[10:11]
	v_lshl_add_u64 v[212:213], v[212:213], 0, s[10:11]
	v_lshl_add_u64 v[214:215], v[214:215], 0, s[10:11]
	ds_read_b128 v[10:13], v8
	ds_read_b128 v[14:17], v8 offset:16
	ds_read_b128 v[18:21], v8 offset:256
	ds_read_b128 v[22:25], v8 offset:272
	ds_read_b128 v[26:29], v8 offset:512
	ds_read_b128 v[30:33], v8 offset:528
	ds_read_b128 v[34:37], v8 offset:768
	ds_read_b128 v[38:41], v8 offset:784
	ds_read_b128 v[42:45], v8 offset:1024
	ds_read_b128 v[46:49], v8 offset:1040
	v_add_u32_e32 v8, 32, v8
	s_waitcnt vmcnt(24) lgkmcnt(0)
	v_fmac_f32_e32 v6, v216, v10
	v_fmac_f32_e32 v7, v216, v18
	v_fmac_f32_e32 v9, v216, v26
	v_fmac_f32_e32 v3, v216, v34
	v_fmac_f32_e32 v2, v216, v42
	v_fmac_f32_e32 v6, v217, v11
	v_fmac_f32_e32 v7, v217, v19
	v_fmac_f32_e32 v9, v217, v27
	v_fmac_f32_e32 v3, v217, v35
	v_fmac_f32_e32 v2, v217, v43
	v_fmac_f32_e32 v6, v218, v12
	v_fmac_f32_e32 v7, v218, v20
	v_fmac_f32_e32 v9, v218, v28
	v_fmac_f32_e32 v3, v218, v36
	v_fmac_f32_e32 v2, v218, v44
	v_fmac_f32_e32 v6, v219, v13
	v_fmac_f32_e32 v7, v219, v21
	v_fmac_f32_e32 v9, v219, v29
	v_fmac_f32_e32 v3, v219, v37
	v_fmac_f32_e32 v2, v219, v45
	v_fmac_f32_e32 v6, v220, v14
	v_fmac_f32_e32 v7, v220, v22
	v_fmac_f32_e32 v9, v220, v30
	v_fmac_f32_e32 v3, v220, v38
	v_fmac_f32_e32 v2, v220, v46
	v_fmac_f32_e32 v6, v221, v15
	v_fmac_f32_e32 v7, v221, v23
	v_fmac_f32_e32 v9, v221, v31
	v_fmac_f32_e32 v3, v221, v39
	v_fmac_f32_e32 v2, v221, v47
	v_fmac_f32_e32 v6, v222, v16
	v_fmac_f32_e32 v7, v222, v24
	v_fmac_f32_e32 v9, v222, v32
	v_fmac_f32_e32 v3, v222, v40
	v_fmac_f32_e32 v2, v222, v48
	v_fmac_f32_e32 v6, v223, v17
	v_fmac_f32_e32 v7, v223, v25
	v_fmac_f32_e32 v9, v223, v33
	v_fmac_f32_e32 v3, v223, v41
	v_fmac_f32_e32 v2, v223, v49
	ds_read_b128 v[10:13], v8
	ds_read_b128 v[14:17], v8 offset:16
	ds_read_b128 v[18:21], v8 offset:256
	ds_read_b128 v[22:25], v8 offset:272
	ds_read_b128 v[26:29], v8 offset:512
	ds_read_b128 v[30:33], v8 offset:528
	ds_read_b128 v[34:37], v8 offset:768
	ds_read_b128 v[38:41], v8 offset:784
	ds_read_b128 v[42:45], v8 offset:1024
	ds_read_b128 v[46:49], v8 offset:1040
	v_add_u32_e32 v8, 32, v8
	s_waitcnt vmcnt(16) lgkmcnt(0)
	v_fmac_f32_e32 v6, v224, v10
	v_fmac_f32_e32 v7, v224, v18
	v_fmac_f32_e32 v9, v224, v26
	v_fmac_f32_e32 v3, v224, v34
	v_fmac_f32_e32 v2, v224, v42
	v_fmac_f32_e32 v6, v225, v11
	v_fmac_f32_e32 v7, v225, v19
	v_fmac_f32_e32 v9, v225, v27
	v_fmac_f32_e32 v3, v225, v35
	v_fmac_f32_e32 v2, v225, v43
	v_fmac_f32_e32 v6, v226, v12
	v_fmac_f32_e32 v7, v226, v20
	v_fmac_f32_e32 v9, v226, v28
	v_fmac_f32_e32 v3, v226, v36
	v_fmac_f32_e32 v2, v226, v44
	v_fmac_f32_e32 v6, v227, v13
	v_fmac_f32_e32 v7, v227, v21
	v_fmac_f32_e32 v9, v227, v29
	v_fmac_f32_e32 v3, v227, v37
	v_fmac_f32_e32 v2, v227, v45
	v_fmac_f32_e32 v6, v228, v14
	v_fmac_f32_e32 v7, v228, v22
	v_fmac_f32_e32 v9, v228, v30
	v_fmac_f32_e32 v3, v228, v38
	v_fmac_f32_e32 v2, v228, v46
	v_fmac_f32_e32 v6, v229, v15
	v_fmac_f32_e32 v7, v229, v23
	v_fmac_f32_e32 v9, v229, v31
	v_fmac_f32_e32 v3, v229, v39
	v_fmac_f32_e32 v2, v229, v47
	v_fmac_f32_e32 v6, v230, v16
	v_fmac_f32_e32 v7, v230, v24
	v_fmac_f32_e32 v9, v230, v32
	v_fmac_f32_e32 v3, v230, v40
	v_fmac_f32_e32 v2, v230, v48
	v_fmac_f32_e32 v6, v231, v17
	v_fmac_f32_e32 v7, v231, v25
	v_fmac_f32_e32 v9, v231, v33
	v_fmac_f32_e32 v3, v231, v41
	v_fmac_f32_e32 v2, v231, v49
	ds_read_b128 v[10:13], v8
	ds_read_b128 v[14:17], v8 offset:16
	ds_read_b128 v[18:21], v8 offset:256
	ds_read_b128 v[22:25], v8 offset:272
	ds_read_b128 v[26:29], v8 offset:512
	ds_read_b128 v[30:33], v8 offset:528
	ds_read_b128 v[34:37], v8 offset:768
	ds_read_b128 v[38:41], v8 offset:784
	ds_read_b128 v[42:45], v8 offset:1024
	ds_read_b128 v[46:49], v8 offset:1040
	v_add_u32_e32 v8, 32, v8
	s_waitcnt vmcnt(8) lgkmcnt(0)
	v_fmac_f32_e32 v6, v240, v10
	v_fmac_f32_e32 v7, v240, v18
	v_fmac_f32_e32 v9, v240, v26
	v_fmac_f32_e32 v3, v240, v34
	v_fmac_f32_e32 v2, v240, v42
	v_fmac_f32_e32 v6, v241, v11
	v_fmac_f32_e32 v7, v241, v19
	v_fmac_f32_e32 v9, v241, v27
	v_fmac_f32_e32 v3, v241, v35
	v_fmac_f32_e32 v2, v241, v43
	v_fmac_f32_e32 v6, v242, v12
	v_fmac_f32_e32 v7, v242, v20
	v_fmac_f32_e32 v9, v242, v28
	v_fmac_f32_e32 v3, v242, v36
	v_fmac_f32_e32 v2, v242, v44
	v_fmac_f32_e32 v6, v243, v13
	v_fmac_f32_e32 v7, v243, v21
	v_fmac_f32_e32 v9, v243, v29
	v_fmac_f32_e32 v3, v243, v37
	v_fmac_f32_e32 v2, v243, v45
	v_fmac_f32_e32 v6, v244, v14
	v_fmac_f32_e32 v7, v244, v22
	v_fmac_f32_e32 v9, v244, v30
	v_fmac_f32_e32 v3, v244, v38
	v_fmac_f32_e32 v2, v244, v46
	v_fmac_f32_e32 v6, v245, v15
	v_fmac_f32_e32 v7, v245, v23
	v_fmac_f32_e32 v9, v245, v31
	v_fmac_f32_e32 v3, v245, v39
	v_fmac_f32_e32 v2, v245, v47
	v_fmac_f32_e32 v6, v246, v16
	v_fmac_f32_e32 v7, v246, v24
	v_fmac_f32_e32 v9, v246, v32
	v_fmac_f32_e32 v3, v246, v40
	v_fmac_f32_e32 v2, v246, v48
	v_fmac_f32_e32 v6, v247, v17
	v_fmac_f32_e32 v7, v247, v25
	v_fmac_f32_e32 v9, v247, v33
	v_fmac_f32_e32 v3, v247, v41
	v_fmac_f32_e32 v2, v247, v49
	ds_read_b128 v[10:13], v8
	ds_read_b128 v[14:17], v8 offset:16
	ds_read_b128 v[18:21], v8 offset:256
	ds_read_b128 v[22:25], v8 offset:272
	ds_read_b128 v[26:29], v8 offset:512
	ds_read_b128 v[30:33], v8 offset:528
	ds_read_b128 v[34:37], v8 offset:768
	ds_read_b128 v[38:41], v8 offset:784
	ds_read_b128 v[42:45], v8 offset:1024
	ds_read_b128 v[46:49], v8 offset:1040
	v_add_u32_e32 v8, 32, v8
	s_waitcnt vmcnt(0) lgkmcnt(0)
	v_fmac_f32_e32 v6, v232, v10
	v_fmac_f32_e32 v7, v232, v18
	v_fmac_f32_e32 v9, v232, v26
	v_fmac_f32_e32 v3, v232, v34
	v_fmac_f32_e32 v2, v232, v42
	v_fmac_f32_e32 v6, v233, v11
	v_fmac_f32_e32 v7, v233, v19
	v_fmac_f32_e32 v9, v233, v27
	v_fmac_f32_e32 v3, v233, v35
	v_fmac_f32_e32 v2, v233, v43
	v_fmac_f32_e32 v6, v234, v12
	v_fmac_f32_e32 v7, v234, v20
	v_fmac_f32_e32 v9, v234, v28
	v_fmac_f32_e32 v3, v234, v36
	v_fmac_f32_e32 v2, v234, v44
	v_fmac_f32_e32 v6, v235, v13
	v_fmac_f32_e32 v7, v235, v21
	v_fmac_f32_e32 v9, v235, v29
	v_fmac_f32_e32 v3, v235, v37
	v_fmac_f32_e32 v2, v235, v45
	v_fmac_f32_e32 v6, v236, v14
	v_fmac_f32_e32 v7, v236, v22
	v_fmac_f32_e32 v9, v236, v30
	v_fmac_f32_e32 v3, v236, v38
	v_fmac_f32_e32 v2, v236, v46
	v_fmac_f32_e32 v6, v237, v15
	v_fmac_f32_e32 v7, v237, v23
	v_fmac_f32_e32 v9, v237, v31
	v_fmac_f32_e32 v3, v237, v39
	v_fmac_f32_e32 v2, v237, v47
	v_fmac_f32_e32 v6, v238, v16
	v_fmac_f32_e32 v7, v238, v24
	v_fmac_f32_e32 v9, v238, v32
	v_fmac_f32_e32 v3, v238, v40
	v_fmac_f32_e32 v2, v238, v48
	v_fmac_f32_e32 v6, v248, v17
	v_fmac_f32_e32 v7, v248, v25
	v_fmac_f32_e32 v9, v248, v33
	v_fmac_f32_e32 v3, v248, v41
	v_fmac_f32_e32 v2, v248, v49
	s_lshl_b32 s7, s25, 2
	s_add_i32 s6, s7, s6
	s_mul_hi_i32 s7, s6, 0xb400
	s_mul_i32 s6, s6, 0xb400
	s_add_u32 s6, s12, s6
	s_addc_u32 s7, s13, s7
	v_lshl_add_u64 v[0:1], v[0:1], 2, s[6:7]
	v_add_co_u32_e32 v4, vcc, 0x2000, v0
	global_store_dword v[0:1], v6, off
	s_nop 0
	v_addc_co_u32_e32 v5, vcc, 0, v1, vcc
	global_store_dword v[4:5], v7, off offset:1024
	v_add_co_u32_e32 v4, vcc, 0x4000, v0
	s_nop 1
	v_addc_co_u32_e32 v5, vcc, 0, v1, vcc
	global_store_dword v[4:5], v9, off offset:2048
	v_add_co_u32_e32 v4, vcc, 0x6000, v0
	s_nop 1
	v_addc_co_u32_e32 v5, vcc, 0, v1, vcc
	v_add_co_u32_e32 v0, vcc, 0x9000, v0
	global_store_dword v[4:5], v3, off offset:3072
	s_nop 0
	v_addc_co_u32_e32 v1, vcc, 0, v1, vcc
	global_store_dword v[0:1], v2, off
	s_branch .LBB0_105

.LBB0_412:
	s_or_b64 exec, exec, s[0:1]
	s_lshl_b32 s0, s86, 17
	v_readlane_b32 s1, v254, 54
	s_or_b32 s0, s0, s1
	s_add_u32 s1, s28, s54
	s_addc_u32 s4, s29, s55
	s_add_u32 s0, s1, s0
	s_waitcnt vmcnt(0)
	v_lshlrev_b32_e32 v0, 3, v21
	s_addc_u32 s1, s4, 0
	v_and_b32_e32 v4, 0xffffff80, v0
	v_lshl_add_u64 v[2:3], s[0:1], 0, v[198:199]
	v_ashrrev_i32_e32 v5, 31, v4
	v_lshl_add_u64 v[6:7], v[4:5], 1, v[2:3]
	v_add_u32_e32 v8, 0x1000, v4
	v_add_u32_e32 v10, 0x2000, v4
	v_add_u32_e32 v4, 0x3000, v4
	v_ashrrev_i32_e32 v9, 31, v8
	v_ashrrev_i32_e32 v11, 31, v10
	v_ashrrev_i32_e32 v5, 31, v4
	v_lshl_add_u64 v[8:9], v[8:9], 1, v[2:3]
	v_lshl_add_u64 v[10:11], v[10:11], 1, v[2:3]
	v_lshl_add_u64 v[12:13], v[4:5], 1, v[2:3]
	global_load_dwordx4 v[2:5], v[6:7], off
	global_load_dwordx4 v[32:35], v[8:9], off
	global_load_dwordx4 v[36:39], v[10:11], off
	global_load_dwordx4 v[40:43], v[12:13], off
	v_mad_u64_u32 v[14:15], s[0:1], v22, s66, v[20:21]
	v_mad_u64_u32 v[6:7], s[0:1], v23, s66, v[20:21]
	v_lshrrev_b32_e32 v0, 1, v21
	v_and_b32_e32 v1, 31, v132
	v_ashrrev_i32_e32 v96, 8, v21
	v_and_b32_e32 v119, 0x60, v0
	v_readlane_b32 s36, v254, 0
	v_lshlrev_b32_e32 v123, 6, v96
	v_readlane_b32 s48, v254, 12
	v_readlane_b32 s49, v254, 13
	v_bfe_u32 v97, v132, 5, 1
	v_readlane_b32 s40, v254, 4
	v_readlane_b32 s41, v254, 5
	s_mov_b64 s[12:13], s[48:49]
	v_readlane_b32 s42, v254, 6
	v_readlane_b32 s43, v254, 7
	v_readlane_b32 s44, v254, 8
	v_readlane_b32 s45, v254, 9
	s_mov_b64 s[4:5], s[40:41]
	s_mov_b64 s[8:9], s[44:45]
	v_ashrrev_i32_e32 v135, 2, v21
	v_and_b32_e32 v134, -16, v135
	v_mul_lo_u32 v133, v134, s66
	v_readlane_b32 s37, v254, 1
	v_readlane_b32 s38, v254, 2
	v_readlane_b32 s39, v254, 3
	v_readlane_b32 s46, v254, 10
	v_readlane_b32 s47, v254, 11
	v_readlane_b32 s50, v254, 14
	v_readlane_b32 s51, v254, 15
	s_mov_b64 s[6:7], s[42:43]
	s_waitcnt vmcnt(3)
	ds_write_b128 v14, v[2:5] offset:39168
	s_waitcnt vmcnt(2)
	ds_write_b128 v6, v[32:35] offset:39168
	v_mad_u64_u32 v[6:7], s[0:1], v24, s66, v[20:21]
	s_waitcnt vmcnt(1)
	ds_write_b128 v6, v[36:39] offset:39168
	v_mad_u64_u32 v[6:7], s[0:1], v25, s66, v[20:21]
	v_readlane_b32 s0, v254, 52
	s_waitcnt vmcnt(0)
	ds_write_b128 v6, v[40:43] offset:39168
	v_or3_b32 v198, v1, s0, v119
	v_readlane_b32 s0, v254, 57
	v_mov_b64_e32 v[2:3], s[52:53]
	s_nop 0
	v_add_u32_e32 v0, s0, v123
	v_mad_u64_u32 v[2:3], s[0:1], v198, s62, v[2:3]
	v_lshl_or_b32 v112, v97, 2, v0
	s_add_u32 s0, s12, s88
	s_addc_u32 s1, s13, s89
	v_ashrrev_i32_e32 v113, 31, v112
	s_add_u32 s4, s8, s88
	v_lshlrev_b64 v[4:5], 2, v[112:113]
	s_addc_u32 s5, s9, s89
	v_lshl_add_u64 v[2:3], v[112:113], 1, v[2:3]
	v_lshl_add_u64 v[6:7], s[0:1], 0, v[4:5]
	global_load_dwordx2 v[114:115], v[2:3], off offset:3584
	v_lshl_add_u64 v[4:5], s[4:5], 0, v[4:5]
	global_load_dwordx4 v[92:95], v[6:7], off
	global_load_dwordx4 v[88:91], v[4:5], off
	global_load_dwordx2 v[110:111], v[2:3], off offset:3600
	global_load_dwordx4 v[84:87], v[6:7], off offset:32
	global_load_dwordx4 v[80:83], v[4:5], off offset:32
	global_load_dwordx2 v[108:109], v[2:3], off offset:3616
	global_load_dwordx4 v[76:79], v[6:7], off offset:64
	global_load_dwordx4 v[72:75], v[4:5], off offset:64
	global_load_dwordx2 v[106:107], v[2:3], off offset:3632
	global_load_dwordx4 v[68:71], v[6:7], off offset:96
	global_load_dwordx4 v[64:67], v[4:5], off offset:96
	global_load_dwordx2 v[104:105], v[2:3], off offset:3648
	global_load_dwordx4 v[60:63], v[6:7], off offset:128
	global_load_dwordx4 v[56:59], v[4:5], off offset:128
	global_load_dwordx2 v[102:103], v[2:3], off offset:3664
	global_load_dwordx4 v[52:55], v[6:7], off offset:160
	global_load_dwordx4 v[48:51], v[4:5], off offset:160
	global_load_dwordx2 v[100:101], v[2:3], off offset:3680
	global_load_dwordx4 v[44:47], v[6:7], off offset:192
	global_load_dwordx4 v[40:43], v[4:5], off offset:192
	global_load_dwordx2 v[98:99], v[2:3], off offset:3696
	global_load_dwordx4 v[36:39], v[6:7], off offset:224
	global_load_dwordx4 v[32:35], v[4:5], off offset:224
	s_cmp_lt_i32 s96, 2
	s_waitcnt lgkmcnt(0)
	s_barrier
	s_cbranch_scc1 .LBB0_422
	s_cmp_gt_i32 s96, 2
	s_mov_b64 s[0:1], -1
	s_cbranch_scc0 .LBB0_415
	v_lshlrev_b32_e32 v0, 2, v132
	v_and_b32_e32 v129, 0xfc, v0
	v_add_u32_e32 v137, v133, v129
	ds_read2_b32 v[2:3], v137 offset1:68
	ds_read2_b32 v[4:5], v137 offset0:136 offset1:204
	v_readlane_b32 s1, v254, 55
	v_or_b32_e32 v122, 1, v134
	v_readlane_b32 s0, v254, 51
	v_add_u32_e32 v124, s1, v122
	v_max_i32_e32 v125, 8, v124
	v_or_b32_e32 v124, 8, v124
	v_add_u32_e32 v0, 0x400, v137
	v_min_i32_e32 v124, s0, v124
	s_waitcnt lgkmcnt(1)
	v_lshlrev_b32_e32 v28, 16, v2
	v_and_b32_e32 v29, 0xffff0000, v2
	v_lshlrev_b32_e32 v26, 16, v3
	v_and_b32_e32 v27, 0xffff0000, v3
	ds_read2_b32 v[2:3], v0 offset0:16 offset1:84
	v_sub_u32_e32 v124, v124, v125
	v_add_u32_e32 v124, 8, v124
	v_cvt_f32_i32_e32 v126, v124
	s_waitcnt lgkmcnt(1)
	v_lshlrev_b32_e32 v24, 16, v4
	v_and_b32_e32 v25, 0xffff0000, v4
	v_lshlrev_b32_e32 v22, 16, v5
	v_and_b32_e32 v23, 0xffff0000, v5
	ds_read2_b32 v[4:5], v0 offset0:152 offset1:220
	v_add_u32_e32 v0, 0x800, v137
	s_waitcnt lgkmcnt(1)
	v_lshlrev_b32_e32 v30, 16, v2
	v_and_b32_e32 v31, 0xffff0000, v2
	v_lshlrev_b32_e32 v20, 16, v3
	v_and_b32_e32 v21, 0xffff0000, v3
	ds_read2_b32 v[2:3], v0 offset0:32 offset1:100
	v_add_u32_e32 v141, s1, v134
	v_mul_lo_u32 v140, v122, s66
	v_rcp_iflag_f32_e32 v122, v126
	v_add_u32_e32 v126, 2, v141
	v_add_u32_e32 v169, 10, v141
	v_add_u32_e32 v130, 3, v141
	v_add_u32_e32 v173, 11, v141
	v_max_i32_e32 v126, 8, v126
	v_min_i32_e32 v127, s0, v169
	v_max_i32_e32 v130, 8, v130
	v_min_i32_e32 v131, s0, v173
	v_sub_u32_e32 v126, v127, v126
	v_sub_u32_e32 v130, v131, v130
	s_waitcnt lgkmcnt(1)
	v_lshlrev_b32_e32 v18, 16, v4
	v_and_b32_e32 v19, 0xffff0000, v4
	v_lshlrev_b32_e32 v16, 16, v5
	v_and_b32_e32 v17, 0xffff0000, v5
	ds_read2_b32 v[4:5], v0 offset0:168 offset1:236
	v_add_u32_e32 v0, 0xc00, v137
	v_add_u32_e32 v126, 8, v126
	v_add_u32_e32 v130, 8, v130
	s_waitcnt lgkmcnt(1)
	v_lshlrev_b32_e32 v14, 16, v2
	v_and_b32_e32 v15, 0xffff0000, v2
	v_lshlrev_b32_e32 v12, 16, v3
	v_and_b32_e32 v13, 0xffff0000, v3
	ds_read2_b32 v[2:3], v0 offset0:48 offset1:116
	ds_read2_b32 v[116:117], v0 offset0:184 offset1:252
	v_cvt_f32_i32_e32 v128, v126
	v_cvt_f32_i32_e32 v138, v130
	v_add_u32_e32 v181, 12, v141
	s_waitcnt lgkmcnt(2)
	v_lshlrev_b32_e32 v10, 16, v4
	v_rcp_iflag_f32_e32 v136, v128
	v_rcp_iflag_f32_e32 v128, v138
	v_add_u32_e32 v138, 4, v141
	v_and_b32_e32 v11, 0xffff0000, v4
	v_lshlrev_b32_e32 v8, 16, v5
	v_and_b32_e32 v9, 0xffff0000, v5
	s_waitcnt lgkmcnt(1)
	v_lshlrev_b32_e32 v6, 16, v2
	v_and_b32_e32 v7, 0xffff0000, v2
	v_lshlrev_b32_e32 v4, 16, v3
	v_and_b32_e32 v5, 0xffff0000, v3
	s_waitcnt lgkmcnt(0)
	v_lshlrev_b32_e32 v2, 16, v116
	v_and_b32_e32 v3, 0xffff0000, v116
	v_or_b32_e32 v116, 8, v141
	v_max_i32_e32 v138, 8, v138
	v_min_i32_e32 v139, s0, v181
	v_max_i32_e32 v0, 8, v141
	v_min_i32_e32 v116, s0, v116
	v_sub_u32_e32 v138, v139, v138
	v_sub_u32_e32 v0, v116, v0
	v_add_u32_e32 v138, 8, v138
	v_add_u32_e32 v0, 8, v0
	v_cvt_f32_i32_e32 v142, v138
	v_add_u32_e32 v138, 0x1400, v137
	v_cvt_f32_i32_e32 v118, v0
	v_or_b32_e32 v0, 0x12100, v129
	ds_read2_b32 v[138:139], v138 offset0:80 offset1:148
	v_add_u32_e32 v144, 0x330, v140
	v_add_u32_e32 v185, v0, v144
	v_add_u32_e32 v194, v144, v129
	v_add_u32_e32 v144, 6, v141
	v_add_u32_e32 v195, 14, v141
	v_max_i32_e32 v146, 8, v144
	v_min_i32_e32 v147, s0, v195
	v_sub_u32_e32 v146, v147, v146
	v_add_u32_e32 v146, 8, v146
	v_cvt_f32_i32_e32 v148, v146
	s_waitcnt lgkmcnt(0)
	v_lshlrev_b32_e32 v146, 16, v139
	v_and_b32_e32 v147, 0xffff0000, v139
	v_add_u32_e32 v139, 0x1600, v137
	ds_read2_b32 v[152:153], v139 offset0:88 offset1:156
	v_add_u32_e32 v139, 7, v141
	v_add_u32_e32 v151, 15, v141
	v_add_u32_e32 v161, v0, v140
	v_rcp_iflag_f32_e32 v140, v142
	v_lshlrev_b32_e32 v142, 16, v138
	v_and_b32_e32 v143, 0xffff0000, v138
	v_add_u32_e32 v138, 5, v141
	v_add_u32_e32 v187, 13, v141
	v_max_i32_e32 v139, 8, v139
	v_min_i32_e32 v151, s0, v151
	v_max_i32_e32 v138, 8, v138
	v_min_i32_e32 v145, s0, v187
	v_add_u32_e32 v144, 0x800, v194
	v_sub_u32_e32 v139, v151, v139
	v_sub_u32_e32 v138, v145, v138
	ds_read2_b32 v[144:145], v144 offset0:168 offset1:236
	v_add_u32_e32 v139, 8, v139
	v_cvt_f32_i32_e32 v139, v139
	s_waitcnt lgkmcnt(1)
	v_lshlrev_b32_e32 v154, 16, v152
	v_and_b32_e32 v155, 0xffff0000, v152
	s_waitcnt lgkmcnt(0)
	v_lshlrev_b32_e32 v150, 16, v144
	v_and_b32_e32 v151, 0xffff0000, v144
	v_rcp_iflag_f32_e32 v144, v139
	v_add_u32_e32 v139, 8, v141
	v_add_u32_e32 v152, 16, v141
	v_max_i32_e32 v139, 8, v139
	v_min_i32_e32 v152, s0, v152
	v_sub_u32_e32 v139, v152, v139
	v_add_u32_e32 v139, 8, v139
	v_cvt_f32_i32_e32 v139, v139
	v_lshlrev_b32_e32 v156, 16, v145
	v_and_b32_e32 v157, 0xffff0000, v145
	v_add_u32_e32 v145, 17, v141
	v_rcp_iflag_f32_e32 v160, v139
	v_add_u32_e32 v139, 0x1800, v137
	ds_read2_b32 v[164:165], v139 offset0:96 offset1:164
	v_add_u32_e32 v139, 9, v141
	v_max_i32_e32 v139, 8, v139
	v_min_i32_e32 v145, s0, v145
	v_add_u32_e32 v170, 0xc00, v194
	v_sub_u32_e32 v139, v145, v139
	ds_read2_b32 v[158:159], v170 offset0:48 offset1:116
	v_add_u32_e32 v139, 8, v139
	v_cvt_f32_i32_e32 v139, v139
	v_add_u32_e32 v145, 18, v141
	v_min_i32_e32 v145, s0, v145
	s_waitcnt lgkmcnt(0)
	v_lshlrev_b32_e32 v162, 16, v158
	v_and_b32_e32 v163, 0xffff0000, v158
	v_rcp_iflag_f32_e32 v158, v139
	v_max_i32_e32 v139, 8, v169
	v_sub_u32_e32 v139, v145, v139
	v_add_u32_e32 v139, 8, v139
	v_cvt_f32_i32_e32 v139, v139
	v_add_u32_e32 v145, 19, v141
	v_min_i32_e32 v145, s0, v145
	ds_read2_b32 v[170:171], v170 offset0:184 offset1:252
	v_rcp_iflag_f32_e32 v172, v139
	v_add_u32_e32 v139, 0x1a00, v137
	ds_read2_b32 v[176:177], v139 offset0:104 offset1:172
	v_max_i32_e32 v139, 8, v173
	v_sub_u32_e32 v139, v145, v139
	v_add_u32_e32 v139, 8, v139
	v_cvt_f32_i32_e32 v139, v139
	v_pk_add_f32 v[204:205], v[28:29], 0 op_sel_hi:[1,0]
	v_add_u32_e32 v145, 20, v141
	v_pk_add_f32 v[204:205], v[204:205], v[26:27]
	s_waitcnt lgkmcnt(1)
	v_lshlrev_b32_e32 v174, 16, v170
	v_pk_add_f32 v[204:205], v[204:205], v[24:25]
	v_and_b32_e32 v175, 0xffff0000, v170
	v_pk_add_f32 v[204:205], v[204:205], v[22:23]
	v_rcp_iflag_f32_e32 v170, v139
	v_max_i32_e32 v139, 8, v181
	v_min_i32_e32 v145, s0, v145
	v_pk_add_f32 v[204:205], v[204:205], v[30:31]
	v_sub_u32_e32 v139, v145, v139
	v_pk_add_f32 v[204:205], v[204:205], v[20:21]
	v_add_u32_e32 v139, 8, v139
	v_pk_add_f32 v[30:31], v[142:143], v[30:31] neg_lo:[0,1] neg_hi:[0,1]
	v_pk_add_f32 v[142:143], v[204:205], v[18:19]
	v_cvt_f32_i32_e32 v139, v139
	v_pk_add_f32 v[142:143], v[142:143], v[16:17]
	v_add_u32_e32 v120, 0x1000, v137
	v_pk_add_f32 v[142:143], v[142:143], v[14:15]
	ds_read2_b32 v[120:121], v120 offset0:64 offset1:132
	v_pk_add_f32 v[142:143], v[142:143], v[12:13]
	v_add_u32_e32 v126, 0x1200, v137
	v_pk_add_f32 v[142:143], v[142:143], v[10:11]
	ds_read2_b32 v[126:127], v126 offset0:72 offset1:140
	v_rcp_iflag_f32_e32 v184, v139
	v_add_u32_e32 v139, 0x1c00, v137
	v_add_u32_e32 v145, 21, v141
	v_pk_add_f32 v[142:143], v[142:143], v[8:9]
	ds_read2_b32 v[188:189], v139 offset0:112 offset1:180
	v_max_i32_e32 v139, 8, v187
	v_min_i32_e32 v145, s0, v145
	v_pk_add_f32 v[142:143], v[142:143], v[6:7]
	v_lshlrev_b32_e32 v168, 16, v159
	v_and_b32_e32 v169, 0xffff0000, v159
	v_add_u32_e32 v159, 0x1000, v194
	v_sub_u32_e32 v139, v145, v139
	v_pk_add_f32 v[142:143], v[142:143], v[4:5]
	v_lshlrev_b32_e32 v116, 16, v117
	v_and_b32_e32 v117, 0xffff0000, v117
	s_waitcnt lgkmcnt(2)
	v_lshlrev_b32_e32 v124, 16, v120
	v_and_b32_e32 v125, 0xffff0000, v120
	ds_read2_b32 v[182:183], v159 offset0:64 offset1:132
	v_add_u32_e32 v139, 8, v139
	v_pk_add_f32 v[142:143], v[142:143], v[2:3]
	v_lshlrev_b32_e32 v120, 16, v121
	v_and_b32_e32 v121, 0xffff0000, v121
	v_cvt_f32_i32_e32 v139, v139
	ds_read_b32 v137, v137 offset:8160
	v_pk_add_f32 v[116:117], v[142:143], v[116:117]
	v_pk_add_f32 v[28:29], v[124:125], v[28:29] neg_lo:[0,1] neg_hi:[0,1]
	v_rcp_iflag_f32_e32 v118, v118
	s_waitcnt lgkmcnt(3)
	v_lshlrev_b32_e32 v130, 16, v126
	v_and_b32_e32 v131, 0xffff0000, v126
	v_pk_add_f32 v[28:29], v[116:117], v[28:29]
	v_pk_add_f32 v[26:27], v[120:121], v[26:27] neg_lo:[0,1] neg_hi:[0,1]
	v_lshlrev_b32_e32 v126, 16, v127
	v_and_b32_e32 v127, 0xffff0000, v127
	v_pk_add_f32 v[26:27], v[28:29], v[26:27]
	v_pk_add_f32 v[24:25], v[130:131], v[24:25] neg_lo:[0,1] neg_hi:[0,1]
	v_add_u32_e32 v141, 22, v141
	v_pk_add_f32 v[24:25], v[26:27], v[24:25]
	v_pk_add_f32 v[22:23], v[126:127], v[22:23] neg_lo:[0,1] neg_hi:[0,1]
	v_add_u32_e32 v138, 8, v138
	s_waitcnt lgkmcnt(1)
	v_lshlrev_b32_e32 v186, 16, v182
	v_and_b32_e32 v187, 0xffff0000, v182
	v_rcp_iflag_f32_e32 v182, v139
	v_max_i32_e32 v139, 8, v195
	v_min_i32_e32 v141, s0, v141
	v_pk_add_f32 v[22:23], v[24:25], v[22:23]
	v_cvt_f32_i32_e32 v138, v138
	v_sub_u32_e32 v139, v141, v139
	v_pk_fma_f32 v[142:143], v[118:119], v[116:117], v[14:15] op_sel_hi:[0,1,1] neg_lo:[0,0,1] neg_hi:[0,0,1]
	v_pk_fma_f32 v[116:117], v[122:123], v[28:29], v[12:13] op_sel_hi:[0,1,1] neg_lo:[0,0,1] neg_hi:[0,0,1]
	s_waitcnt lgkmcnt(0)
	v_pk_fma_f32 v[28:29], v[136:137], v[26:27], v[10:11] op_sel_hi:[0,1,1] neg_lo:[0,0,1] neg_hi:[0,0,1]
	v_pk_fma_f32 v[26:27], v[128:129], v[24:25], v[8:9] op_sel_hi:[0,1,1] neg_lo:[0,0,1] neg_hi:[0,0,1]
	v_pk_fma_f32 v[24:25], v[140:141], v[22:23], v[6:7] op_sel_hi:[0,1,1] neg_lo:[0,0,1] neg_hi:[0,0,1]
	v_pk_add_f32 v[22:23], v[22:23], v[30:31]
	v_pk_add_f32 v[20:21], v[146:147], v[20:21] neg_lo:[0,1] neg_hi:[0,1]
	v_lshlrev_b32_e32 v152, 16, v153
	v_and_b32_e32 v153, 0xffff0000, v153
	v_add_u32_e32 v139, 8, v139
	v_pk_add_f32 v[20:21], v[22:23], v[20:21]
	v_pk_add_f32 v[18:19], v[154:155], v[18:19] neg_lo:[0,1] neg_hi:[0,1]
	v_lshlrev_b32_e32 v166, 16, v164
	v_and_b32_e32 v167, 0xffff0000, v164
	v_cvt_f32_i32_e32 v139, v139
	v_pk_add_f32 v[18:19], v[20:21], v[18:19]
	v_pk_add_f32 v[16:17], v[152:153], v[16:17] neg_lo:[0,1] neg_hi:[0,1]
	v_lshlrev_b32_e32 v164, 16, v165
	v_and_b32_e32 v165, 0xffff0000, v165
	ds_read_b32 v145, v194 offset:4896
	v_pk_add_f32 v[16:17], v[18:19], v[16:17]
	v_pk_add_f32 v[14:15], v[166:167], v[14:15] neg_lo:[0,1] neg_hi:[0,1]
	v_rcp_iflag_f32_e32 v138, v138
	v_rcp_iflag_f32_e32 v148, v148
	v_lshlrev_b32_e32 v178, 16, v176
	v_and_b32_e32 v179, 0xffff0000, v176
	v_pk_add_f32 v[14:15], v[16:17], v[14:15]
	v_pk_add_f32 v[12:13], v[164:165], v[12:13] neg_lo:[0,1] neg_hi:[0,1]
	v_lshlrev_b32_e32 v176, 16, v177
	v_and_b32_e32 v177, 0xffff0000, v177
	v_pk_add_f32 v[12:13], v[14:15], v[12:13]
	v_pk_add_f32 v[10:11], v[178:179], v[10:11] neg_lo:[0,1] neg_hi:[0,1]
	v_lshlrev_b32_e32 v190, 16, v188
	v_and_b32_e32 v191, 0xffff0000, v188
	v_rcp_iflag_f32_e32 v194, v139
	v_pk_add_f32 v[10:11], v[12:13], v[10:11]
	v_pk_add_f32 v[8:9], v[176:177], v[8:9] neg_lo:[0,1] neg_hi:[0,1]
	v_add_u32_e32 v149, v0, v133
	v_lshlrev_b32_e32 v188, 16, v189
	v_and_b32_e32 v189, 0xffff0000, v189
	v_cvt_pk_bf16_f32 v26, v26, v27
	v_pk_add_f32 v[8:9], v[10:11], v[8:9]
	v_pk_add_f32 v[6:7], v[190:191], v[6:7] neg_lo:[0,1] neg_hi:[0,1]
	ds_write_b32 v161, v26 offset:544
	v_cvt_pk_bf16_f32 v26, v24, v25
	v_pk_fma_f32 v[24:25], v[138:139], v[22:23], v[4:5] op_sel_hi:[0,1,1] neg_lo:[0,0,1] neg_hi:[0,0,1]
	v_pk_fma_f32 v[22:23], v[148:149], v[20:21], v[150:151] op_sel_hi:[0,1,1] neg_lo:[0,0,1] neg_hi:[0,0,1]
	s_waitcnt lgkmcnt(1)
	v_pk_fma_f32 v[20:21], v[144:145], v[18:19], v[156:157] op_sel_hi:[0,1,1] neg_lo:[0,0,1] neg_hi:[0,0,1]
	v_pk_add_f32 v[6:7], v[8:9], v[6:7]
	v_pk_add_f32 v[4:5], v[188:189], v[4:5] neg_lo:[0,1] neg_hi:[0,1]
	v_lshlrev_b32_e32 v180, 16, v171
	v_and_b32_e32 v181, 0xffff0000, v171
	v_lshlrev_b32_e32 v192, 16, v183
	v_and_b32_e32 v193, 0xffff0000, v183
	v_lshlrev_b32_e32 v200, 16, v145
	v_and_b32_e32 v201, 0xffff0000, v145
	v_and_b32_e32 v203, 0xffff0000, v137
	v_lshlrev_b32_e32 v202, 16, v137
	v_cvt_pk_bf16_f32 v118, v142, v143
	v_cvt_pk_bf16_f32 v116, v116, v117
	v_cvt_pk_bf16_f32 v28, v28, v29
	v_cvt_pk_bf16_f32 v24, v24, v25
	v_cvt_pk_bf16_f32 v22, v22, v23
	v_cvt_pk_bf16_f32 v20, v20, v21
	v_pk_add_f32 v[4:5], v[6:7], v[4:5]
	ds_write_b32 v149, v118
	ds_write2_b32 v161, v116, v28 offset1:68
	ds_write2_b32 v185, v26, v24 offset1:68
	ds_write2_b32 v185, v22, v20 offset0:136 offset1:204
	v_pk_fma_f32 v[18:19], v[160:161], v[16:17], v[162:163] op_sel_hi:[0,1,1] neg_lo:[0,0,1] neg_hi:[0,0,1]
	v_pk_fma_f32 v[16:17], v[158:159], v[14:15], v[168:169] op_sel_hi:[0,1,1] neg_lo:[0,0,1] neg_hi:[0,0,1]
	v_pk_fma_f32 v[14:15], v[172:173], v[12:13], v[174:175] op_sel_hi:[0,1,1] neg_lo:[0,0,1] neg_hi:[0,0,1]
	v_pk_fma_f32 v[12:13], v[170:171], v[10:11], v[180:181] op_sel_hi:[0,1,1] neg_lo:[0,0,1] neg_hi:[0,0,1]
	v_pk_fma_f32 v[10:11], v[184:185], v[8:9], v[186:187] op_sel_hi:[0,1,1] neg_lo:[0,0,1] neg_hi:[0,0,1]
	v_pk_fma_f32 v[8:9], v[182:183], v[6:7], v[192:193] op_sel_hi:[0,1,1] neg_lo:[0,0,1] neg_hi:[0,0,1]
	v_pk_fma_f32 v[6:7], v[194:195], v[4:5], v[200:201] op_sel_hi:[0,1,1] neg_lo:[0,0,1] neg_hi:[0,0,1]
	v_pk_add_f32 v[2:3], v[202:203], v[2:3] neg_lo:[0,1] neg_hi:[0,1]
	v_or_b32_e32 v22, 15, v135
	v_cvt_pk_bf16_f32 v18, v18, v19
	v_cvt_pk_bf16_f32 v16, v16, v17
	v_add_u32_e32 v17, 0x400, v185
	v_cvt_pk_bf16_f32 v14, v14, v15
	v_cvt_pk_bf16_f32 v12, v12, v13
	v_cvt_pk_bf16_f32 v10, v10, v11
	v_cvt_pk_bf16_f32 v8, v8, v9
	v_add_u32_e32 v9, 0x800, v185
	v_cvt_pk_bf16_f32 v6, v6, v7
	v_pk_add_f32 v[2:3], v[4:5], v[2:3]
	v_add_u32_e32 v4, s1, v22
	ds_write2_b32 v17, v18, v16 offset0:16 offset1:84
	ds_write2_b32 v17, v14, v12 offset0:152 offset1:220
	ds_write2_b32 v9, v10, v8 offset0:32 offset1:100
	ds_write_b32 v185, v6 offset:2720
	v_max_i32_e32 v21, 8, v4
	v_add_u32_e32 v23, 8, v4
	s_mov_b64 s[0:1], 0

.LBB0_430:
	s_and_b64 vcc, exec, s[0:1]
	s_cbranch_vccz .LBB0_444
	s_mov_b64 s[0:1], 0x697b000
	s_mov_b64 s[6:7], 0x9f7b000
	s_mov_b64 s[4:5], 0xb83b000
	v_mbcnt_lo_u32_b32 v19, -1, 0
	v_mbcnt_hi_u32_b32 v19, -1, v19
	s_add_u32 s0, s28, s0
	v_add_u32_e32 v26, s3, v19
	v_ashrrev_i32_e32 v27, 3, v26
	s_addc_u32 s1, s29, s1
	v_readlane_b32 s10, v254, 62
	v_readlane_b32 s8, v254, 60
	v_and_b32_e32 v30, 7, v19
	v_lshlrev_b32_e32 v18, 4, v30
	s_lshl_b32 s68, s8, 1
	s_waitcnt lgkmcnt(0)
	v_add_u32_e32 v33, s10, v27
	v_mov_b64_e32 v[34:35], s[0:1]
	v_mad_i64_i32 v[34:35], s[10:11], v33, s62, v[34:35]
	v_lshlrev_b32_e32 v33, 4, v19
	v_lshl_add_u64 v[34:35], v[34:35], 0, s[68:69]
	v_and_b32_e32 v198, 0x70, v33
	v_lshl_add_u64 v[38:39], v[34:35], 0, v[198:199]
	s_mov_b64 s[8:9], 0x48000
	v_lshl_add_u64 v[40:41], v[38:39], 0, s[8:9]
	v_lshl_add_u64 v[42:43], v[40:41], 0, s[8:9]
	v_lshl_add_u64 v[44:45], v[42:43], 0, s[8:9]
	global_load_dwordx4 v[202:205], v[38:39], off offset:1024
	global_load_dwordx4 v[218:221], v[38:39], off offset:1280
	global_load_dwordx4 v[206:209], v[40:41], off offset:1024
	global_load_dwordx4 v[222:225], v[40:41], off offset:1280
	global_load_dwordx4 v[210:213], v[42:43], off offset:1024
	global_load_dwordx4 v[226:229], v[42:43], off offset:1280
	global_load_dwordx4 v[214:217], v[44:45], off offset:1024
	global_load_dwordx4 v[230:233], v[44:45], off offset:1280
	s_movk_i32 s8, 0x1430
	v_mad_u32_u24 v30, v30, s8, v18
	v_lshrrev_b32_e32 v0, 6, v26
	v_readlane_b32 s8, v254, 61
	v_and_b32_e32 v6, 31, v19
	v_and_b32_e32 v1, 0xffffffe0, v27
	v_and_or_b32 v129, v0, 3, s8
	v_readlane_b32 s8, v254, 63
	v_bfe_u32 v7, v19, 5, 1
	v_lshlrev_b32_e32 v198, 7, v129
	v_or_b32_e32 v0, s8, v6
	v_add_u32_e32 v112, v0, v1
	v_mov_b64_e32 v[0:1], s[0:1]
	v_mad_i64_i32 v[0:1], s[0:1], v112, s62, v[0:1]
	v_lshl_add_u64 v[0:1], v[0:1], 0, v[198:199]
	v_lshlrev_b32_e32 v2, 4, v7
	v_mov_b32_e32 v3, v199
	v_lshl_add_u64 v[4:5], v[0:1], 0, v[2:3]
	v_lshlrev_b32_e32 v198, 3, v7
	global_load_dwordx4 v[96:99], v[4:5], off
	global_load_dwordx4 v[100:103], v[4:5], off offset:32
	global_load_dwordx4 v[104:107], v[4:5], off offset:64
	global_load_dwordx4 v[108:111], v[4:5], off offset:96
	v_lshlrev_b32_e32 v4, 8, v129
	v_mov_b32_e32 v5, v199
	v_lshl_add_u64 v[0:1], v[0:1], 0, v[198:199]
	v_lshl_add_u64 v[4:5], s[90:91], 0, v[4:5]
	v_lshl_add_u64 v[4:5], v[4:5], 0, v[2:3]
	global_load_dwordx2 v[130:131], v[0:1], off offset:1536
	global_load_dwordx4 v[92:95], v[4:5], off
	global_load_dwordx2 v[126:127], v[0:1], off offset:1552
	global_load_dwordx4 v[88:91], v[4:5], off offset:32
	global_load_dwordx2 v[124:125], v[0:1], off offset:1568
	global_load_dwordx4 v[84:87], v[4:5], off offset:64
	global_load_dwordx2 v[122:123], v[0:1], off offset:1584
	global_load_dwordx4 v[80:83], v[4:5], off offset:96
	global_load_dwordx2 v[120:121], v[0:1], off offset:1600
	global_load_dwordx4 v[76:79], v[4:5], off offset:128
	global_load_dwordx2 v[118:119], v[0:1], off offset:1616
	global_load_dwordx4 v[72:75], v[4:5], off offset:160
	global_load_dwordx2 v[116:117], v[0:1], off offset:1632
	global_load_dwordx4 v[68:71], v[4:5], off offset:192
	global_load_dwordx2 v[114:115], v[0:1], off offset:1648
	global_load_dwordx4 v[64:67], v[4:5], off offset:224
	v_readlane_b32 s36, v254, 0
	v_or_b32_e32 v0, s20, v129
	v_mov_b32_e32 v1, v199
	v_readlane_b32 s40, v254, 4
	v_readlane_b32 s41, v254, 5
	v_cmp_eq_u32_e32 vcc, 0, v7
	v_mov_b32_e32 v16, 0
	v_lshl_add_u64 v[0:1], v[0:1], 2, s[40:41]
	global_load_dword v0, v[0:1], off
	s_waitcnt vmcnt(21)
	v_mad_u32_u24 v42, v27, s2, v18
	v_lshl_add_u32 v33, v27, 1, v30
	ds_write_b128 v42, v[202:205]
	ds_write_b16 v33, v218 offset:46080
	ds_write_b16_d16_hi v33, v218 offset:46728
	ds_write_b16 v33, v219 offset:47376
	ds_write_b16_d16_hi v33, v219 offset:48024
	ds_write_b16 v33, v220 offset:48672
	ds_write_b16_d16_hi v33, v220 offset:49320
	ds_write_b16 v33, v221 offset:49968
	ds_write_b16_d16_hi v33, v221 offset:50616
	ds_write_b128 v42, v[206:209] offset:9216
	ds_write_b16 v33, v222 offset:46208
	ds_write_b16_d16_hi v33, v222 offset:46856
	ds_write_b16 v33, v223 offset:47504
	ds_write_b16_d16_hi v33, v223 offset:48152
	ds_write_b16 v33, v224 offset:48800
	ds_write_b16_d16_hi v33, v224 offset:49448
	ds_write_b16 v33, v225 offset:50096
	ds_write_b16_d16_hi v33, v225 offset:50744
	ds_write_b128 v42, v[210:213] offset:18432
	ds_write_b16 v33, v226 offset:46336
	ds_write_b16_d16_hi v33, v226 offset:46984
	ds_write_b16 v33, v227 offset:47632
	ds_write_b16_d16_hi v33, v227 offset:48280
	ds_write_b16 v33, v228 offset:48928
	ds_write_b16_d16_hi v33, v228 offset:49576
	ds_write_b16 v33, v229 offset:50224
	ds_write_b16_d16_hi v33, v229 offset:50872
	ds_write_b128 v42, v[214:217] offset:27648
	ds_write_b16 v33, v230 offset:46464
	ds_write_b16_d16_hi v33, v230 offset:47112
	ds_write_b16 v33, v231 offset:47760
	ds_write_b16_d16_hi v33, v231 offset:48408
	ds_write_b16 v33, v232 offset:49056
	ds_write_b16_d16_hi v33, v232 offset:49704
	ds_write_b16 v33, v233 offset:50352
	ds_write_b16_d16_hi v33, v233 offset:51000
	v_and_b32_e32 v1, 64, v251
	v_add_u32_e32 v1, 64, v1
	v_ashrrev_i32_e32 v113, 31, v112
	v_lshlrev_b32_e32 v132, 6, v129
	v_lshlrev_b32_e32 v128, 2, v7
	s_mov_b32 s8, 0
	v_cndmask_b32_e64 v48, 0, 1.0, vcc
	v_mad_u32_u24 v136, v6, s2, v2
	v_mov_b32_e32 v17, v16
	v_mov_b32_e32 v18, v16
	v_mov_b32_e32 v19, v16
	v_mov_b32_e32 v20, v16
	v_mov_b32_e32 v21, v16
	v_mov_b32_e32 v22, v16
	v_mov_b32_e32 v23, v16
	v_mov_b32_e32 v24, v16
	v_mov_b32_e32 v25, v16
	v_mov_b32_e32 v26, v16
	v_mov_b32_e32 v27, v16
	v_mov_b32_e32 v28, v16
	v_mov_b32_e32 v29, v16
	v_mov_b32_e32 v30, v16
	v_mov_b32_e32 v31, v16
	v_mov_b32_e32 v2, v16
	v_mov_b32_e32 v3, v16
	v_mov_b32_e32 v4, v16
	v_mov_b32_e32 v5, v16
	v_mov_b32_e32 v7, v16
	v_mov_b32_e32 v8, v16
	v_mov_b32_e32 v9, v16
	v_mov_b32_e32 v10, v16
	v_mov_b32_e32 v11, v16
	v_mov_b32_e32 v12, v16
	v_mov_b32_e32 v13, v16
	v_mov_b32_e32 v14, v16
	v_mov_b32_e32 v15, v16
	v_readlane_b32 s37, v254, 1
	v_readlane_b32 s38, v254, 2
	v_readlane_b32 s39, v254, 3
	v_readlane_b32 s42, v254, 6
	v_readlane_b32 s43, v254, 7
	v_readlane_b32 s44, v254, 8
	v_readlane_b32 s45, v254, 9
	v_readlane_b32 s46, v254, 10
	v_readlane_b32 s47, v254, 11
	v_readlane_b32 s48, v254, 12
	v_readlane_b32 s49, v254, 13
	v_readlane_b32 s50, v254, 14
	v_readlane_b32 s51, v254, 15
	s_waitcnt lgkmcnt(0)
	s_barrier
	s_waitcnt vmcnt(0)
	v_mul_f32_e32 v137, 0x3fb8aa3b, v0
	v_xor_b32_e32 v0, 32, v251
	v_cmp_lt_i32_e64 s[0:1], v0, v1
	v_mov_b32_e32 v1, v16
	s_nop 0
	v_cndmask_b32_e64 v0, v251, v0, s[0:1]
	s_movk_i32 s0, 0x288
	v_lshlrev_b32_e32 v133, 2, v0
	v_mad_u32_u24 v135, v6, s0, v198
	v_mov_b32_e32 v0, v16
	v_mov_b32_e32 v6, v16
	v_mov_b32_e32 v244, v48
	s_mov_b32 s21, 4
	v_add_u32_e32 v234, 0xb400, v135
	v_add_u32_e32 v235, 0x10500, v135
	ds_read_b128 v[202:205], v136
	ds_read_b128 v[206:209], v136 offset:32
	ds_read_b128 v[210:213], v136 offset:64
	ds_read_b128 v[214:217], v136 offset:96
	ds_read_b128 v[218:221], v136 offset:4608
	ds_read_b128 v[222:225], v136 offset:4640
	ds_read_b128 v[226:229], v136 offset:4672
	ds_read_b128 v[230:233], v136 offset:4704
	v_add_u32_e32 v136, 0x2400, v136
.Lctx_top:
	s_waitcnt lgkmcnt(7)
	v_mfma_f32_32x32x16_bf16 v[48:63], v[202:205], v[96:99], 0
	ds_read2_b64 v[202:205], v234 offset1:2
	s_waitcnt lgkmcnt(7)
	v_mfma_f32_32x32x16_bf16 v[48:63], v[206:209], v[100:103], v[48:63]
	ds_read2_b64 v[206:209], v234 offset0:4 offset1:6
	s_waitcnt lgkmcnt(7)
	v_mfma_f32_32x32x16_bf16 v[48:63], v[210:213], v[104:107], v[48:63]
	ds_read2_b64 v[210:213], v235 offset1:2
	s_waitcnt lgkmcnt(7)
	v_mfma_f32_32x32x16_bf16 v[48:63], v[214:217], v[108:111], v[48:63]
	ds_read2_b64 v[214:217], v235 offset0:4 offset1:6
	s_waitcnt lgkmcnt(7)
	v_mfma_f32_32x32x16_bf16 v[32:47], v[218:221], v[96:99], 0
	ds_read2_b64 v[218:221], v234 offset0:8 offset1:10
	s_waitcnt lgkmcnt(7)
	v_mfma_f32_32x32x16_bf16 v[32:47], v[222:225], v[100:103], v[32:47]
	ds_read2_b64 v[222:225], v234 offset0:12 offset1:14
	s_waitcnt lgkmcnt(7)
	v_mfma_f32_32x32x16_bf16 v[32:47], v[226:229], v[104:107], v[32:47]
	ds_read2_b64 v[226:229], v235 offset0:8 offset1:10
	s_waitcnt lgkmcnt(7)
	v_mfma_f32_32x32x16_bf16 v[32:47], v[230:233], v[108:111], v[32:47]
	ds_read2_b64 v[230:233], v235 offset0:12 offset1:14
	v_max3_f32 v236, v48, s16, v49
	v_max3_f32 v236, v236, v50, v51
	v_max3_f32 v236, v236, v52, v53
	v_max3_f32 v236, v236, v54, v55
	v_max3_f32 v236, v236, v56, v57
	v_max3_f32 v236, v236, v58, v59
	v_max3_f32 v236, v236, v60, v61
	v_max3_f32 v236, v236, v62, v63
	s_nop 3
	v_max3_f32 v236, v236, v32, v33
	v_max3_f32 v236, v236, v34, v35
	v_max3_f32 v236, v236, v36, v37
	v_max3_f32 v236, v236, v38, v39
	v_max3_f32 v236, v236, v40, v41
	v_max3_f32 v236, v236, v42, v43
	v_max3_f32 v236, v236, v44, v45
	v_max3_f32 v236, v236, v46, v47
	ds_bpermute_b32 v237, v133, v236
	s_waitcnt lgkmcnt(0)
	v_max3_f32 v236, v137, v236, v237
	v_sub_f32_e32 v238, v137, v236
	v_pk_add_f32 v[48:49], v[48:49], v[236:237] op_sel_hi:[1,0] neg_lo:[0,1] neg_hi:[0,1]
	v_pk_add_f32 v[50:51], v[50:51], v[236:237] op_sel_hi:[1,0] neg_lo:[0,1] neg_hi:[0,1]
	v_pk_add_f32 v[52:53], v[52:53], v[236:237] op_sel_hi:[1,0] neg_lo:[0,1] neg_hi:[0,1]
	v_pk_add_f32 v[54:55], v[54:55], v[236:237] op_sel_hi:[1,0] neg_lo:[0,1] neg_hi:[0,1]
	v_pk_add_f32 v[56:57], v[56:57], v[236:237] op_sel_hi:[1,0] neg_lo:[0,1] neg_hi:[0,1]
	v_pk_add_f32 v[58:59], v[58:59], v[236:237] op_sel_hi:[1,0] neg_lo:[0,1] neg_hi:[0,1]
	v_pk_add_f32 v[60:61], v[60:61], v[236:237] op_sel_hi:[1,0] neg_lo:[0,1] neg_hi:[0,1]
	v_pk_add_f32 v[62:63], v[62:63], v[236:237] op_sel_hi:[1,0] neg_lo:[0,1] neg_hi:[0,1]
	v_exp_f32_e32 v238, v238
	v_exp_f32_e32 v48, v48
	v_exp_f32_e32 v49, v49
	v_exp_f32_e32 v50, v50
	v_exp_f32_e32 v51, v51
	v_exp_f32_e32 v52, v52
	v_exp_f32_e32 v53, v53
	v_exp_f32_e32 v54, v54
	v_exp_f32_e32 v55, v55
	v_exp_f32_e32 v56, v56
	v_exp_f32_e32 v57, v57
	v_exp_f32_e32 v58, v58
	v_exp_f32_e32 v59, v59
	v_exp_f32_e32 v60, v60
	v_exp_f32_e32 v61, v61
	v_exp_f32_e32 v62, v62
	v_exp_f32_e32 v63, v63
	v_pk_add_f32 v[242:243], v[48:49], 0 op_sel_hi:[1,0]
	v_pk_add_f32 v[242:243], v[50:51], v[242:243]
	v_pk_add_f32 v[242:243], v[52:53], v[242:243]
	v_pk_add_f32 v[242:243], v[54:55], v[242:243]
	v_pk_add_f32 v[242:243], v[56:57], v[242:243]
	v_pk_add_f32 v[242:243], v[58:59], v[242:243]
	v_pk_add_f32 v[242:243], v[60:61], v[242:243]
	v_pk_add_f32 v[242:243], v[62:63], v[242:243]
	v_cvt_pk_bf16_f32 v48, v48, v49
	v_cvt_pk_bf16_f32 v49, v50, v51
	v_cvt_pk_bf16_f32 v50, v52, v53
	v_cvt_pk_bf16_f32 v51, v54, v55
	v_cvt_pk_bf16_f32 v52, v56, v57
	v_cvt_pk_bf16_f32 v53, v58, v59
	v_cvt_pk_bf16_f32 v54, v60, v61
	v_cvt_pk_bf16_f32 v55, v62, v63
	v_pk_mul_f32 v[16:17], v[16:17], v[238:239] op_sel_hi:[1,0]
	v_pk_mul_f32 v[18:19], v[18:19], v[238:239] op_sel_hi:[1,0]
	v_pk_mul_f32 v[20:21], v[20:21], v[238:239] op_sel_hi:[1,0]
	v_pk_mul_f32 v[22:23], v[22:23], v[238:239] op_sel_hi:[1,0]
	v_pk_mul_f32 v[24:25], v[24:25], v[238:239] op_sel_hi:[1,0]
	v_pk_mul_f32 v[26:27], v[26:27], v[238:239] op_sel_hi:[1,0]
	v_pk_mul_f32 v[28:29], v[28:29], v[238:239] op_sel_hi:[1,0]
	v_pk_mul_f32 v[30:31], v[30:31], v[238:239] op_sel_hi:[1,0]
	v_pk_mul_f32 v[0:1], v[0:1], v[238:239] op_sel_hi:[1,0]
	v_pk_mul_f32 v[2:3], v[2:3], v[238:239] op_sel_hi:[1,0]
	v_pk_mul_f32 v[4:5], v[4:5], v[238:239] op_sel_hi:[1,0]
	v_pk_mul_f32 v[6:7], v[6:7], v[238:239] op_sel_hi:[1,0]
	v_pk_mul_f32 v[8:9], v[8:9], v[238:239] op_sel_hi:[1,0]
	v_pk_mul_f32 v[10:11], v[10:11], v[238:239] op_sel_hi:[1,0]
	v_pk_mul_f32 v[12:13], v[12:13], v[238:239] op_sel_hi:[1,0]
	v_pk_mul_f32 v[14:15], v[14:15], v[238:239] op_sel_hi:[1,0]
	v_mfma_f32_32x32x16_bf16 v[16:31], v[202:205], v[48:51], v[16:31]
	ds_read_b128 v[202:205], v136
	v_pk_add_f32 v[32:33], v[32:33], v[236:237] op_sel_hi:[1,0] neg_lo:[0,1] neg_hi:[0,1]
	v_pk_add_f32 v[34:35], v[34:35], v[236:237] op_sel_hi:[1,0] neg_lo:[0,1] neg_hi:[0,1]
	v_pk_add_f32 v[36:37], v[36:37], v[236:237] op_sel_hi:[1,0] neg_lo:[0,1] neg_hi:[0,1]
	v_pk_add_f32 v[38:39], v[38:39], v[236:237] op_sel_hi:[1,0] neg_lo:[0,1] neg_hi:[0,1]
	v_pk_add_f32 v[40:41], v[40:41], v[236:237] op_sel_hi:[1,0] neg_lo:[0,1] neg_hi:[0,1]
	v_pk_add_f32 v[42:43], v[42:43], v[236:237] op_sel_hi:[1,0] neg_lo:[0,1] neg_hi:[0,1]
	v_pk_add_f32 v[44:45], v[44:45], v[236:237] op_sel_hi:[1,0] neg_lo:[0,1] neg_hi:[0,1]
	v_pk_add_f32 v[46:47], v[46:47], v[236:237] op_sel_hi:[1,0] neg_lo:[0,1] neg_hi:[0,1]
	v_exp_f32_e32 v32, v32
	v_exp_f32_e32 v33, v33
	v_mfma_f32_32x32x16_bf16 v[16:31], v[206:209], v[52:55], v[16:31]
	ds_read_b128 v[206:209], v136 offset:32
	v_exp_f32_e32 v34, v34
	v_exp_f32_e32 v35, v35
	v_exp_f32_e32 v36, v36
	v_exp_f32_e32 v37, v37
	v_exp_f32_e32 v38, v38
	v_exp_f32_e32 v39, v39
	v_exp_f32_e32 v40, v40
	v_exp_f32_e32 v41, v41
	v_exp_f32_e32 v42, v42
	v_exp_f32_e32 v43, v43
	v_mfma_f32_32x32x16_bf16 v[0:15], v[210:213], v[48:51], v[0:15]
	ds_read_b128 v[210:213], v136 offset:64
	v_exp_f32_e32 v44, v44
	v_exp_f32_e32 v45, v45
	v_exp_f32_e32 v46, v46
	v_exp_f32_e32 v47, v47
	v_pk_add_f32 v[242:243], v[32:33], v[242:243]
	v_pk_add_f32 v[242:243], v[34:35], v[242:243]
	v_pk_add_f32 v[242:243], v[36:37], v[242:243]
	v_pk_add_f32 v[242:243], v[38:39], v[242:243]
	v_pk_add_f32 v[242:243], v[40:41], v[242:243]
	v_pk_add_f32 v[242:243], v[42:43], v[242:243]
	v_mfma_f32_32x32x16_bf16 v[0:15], v[214:217], v[52:55], v[0:15]
	ds_read_b128 v[214:217], v136 offset:96
	v_pk_add_f32 v[242:243], v[44:45], v[242:243]
	v_pk_add_f32 v[242:243], v[46:47], v[242:243]
	v_cvt_pk_bf16_f32 v32, v32, v33
	v_cvt_pk_bf16_f32 v33, v34, v35
	v_cvt_pk_bf16_f32 v34, v36, v37
	v_cvt_pk_bf16_f32 v35, v38, v39
	v_cvt_pk_bf16_f32 v36, v40, v41
	v_cvt_pk_bf16_f32 v37, v42, v43
	v_cvt_pk_bf16_f32 v38, v44, v45
	v_cvt_pk_bf16_f32 v39, v46, v47
	v_add_f32_e32 v242, v242, v243
	v_fmac_f32_e32 v242, v244, v238
	v_mfma_f32_32x32x16_bf16 v[16:31], v[218:221], v[32:35], v[16:31]
	ds_read_b128 v[218:221], v136 offset:4608
	v_mfma_f32_32x32x16_bf16 v[16:31], v[222:225], v[36:39], v[16:31]
	ds_read_b128 v[222:225], v136 offset:4640
	v_mfma_f32_32x32x16_bf16 v[0:15], v[226:229], v[32:35], v[0:15]
	ds_read_b128 v[226:229], v136 offset:4672
	v_mfma_f32_32x32x16_bf16 v[0:15], v[230:233], v[36:39], v[0:15]
	ds_read_b128 v[230:233], v136 offset:4704
	v_mov_b32_e32 v244, v242
	v_mov_b32_e32 v137, v236
	v_add_u32_e32 v136, 0x2400, v136
	v_add_u32_e32 v234, 0x80, v234
	v_add_u32_e32 v235, 0x80, v235
	s_add_i32 s21, s21, -1
	s_cmp_lg_u32 s21, 0
	s_cbranch_scc1 .Lctx_top
	v_mov_b32_e32 v48, v244
	ds_bpermute_b32 v32, v133, v48
	s_add_u32 s0, s28, s6
	s_addc_u32 s1, s29, s7
	v_lshlrev_b64 v[34:35], 11, v[112:113]
	v_lshl_add_u64 v[34:35], s[0:1], 0, v[34:35]
	s_waitcnt lgkmcnt(0)
	v_add_f32_e32 v32, v48, v32
	v_rcp_f32_e32 v32, v32
	v_lshlrev_b32_e32 v198, 1, v132
	v_lshl_add_u64 v[36:37], v[34:35], 0, v[198:199]
	v_lshlrev_b32_e32 v34, 16, v130
	v_pk_mul_f32 v[38:39], v[16:17], v[32:33] op_sel_hi:[1,0]
	v_mul_f32_e32 v33, 0xbfb8aa3b, v34
	v_exp_f32_e32 v33, v33
	v_and_b32_e32 v35, 0xffff0000, v130
	v_pk_mul_f32 v[16:17], v[38:39], v[38:39]
	v_pk_mul_f32 v[38:39], v[92:93], v[38:39]
	v_add_f32_e32 v33, 1.0, v33
	v_rcp_f32_e32 v40, v33
	v_mul_f32_e32 v33, 0xbfb8aa3b, v35
	v_exp_f32_e32 v33, v33
	v_lshlrev_b32_e32 v198, 1, v128
	v_add_f32_e32 v16, v16, v17
	v_add_f32_e32 v33, 1.0, v33
	v_rcp_f32_e32 v41, v33
	v_pk_mul_f32 v[18:19], v[18:19], v[32:33] op_sel_hi:[1,0]
	v_pk_mul_f32 v[34:35], v[40:41], v[34:35]
	v_lshlrev_b32_e32 v40, 16, v131
	v_mul_f32_e32 v33, 0xbfb8aa3b, v40
	v_exp_f32_e32 v33, v33
	v_and_b32_e32 v41, 0xffff0000, v131
	v_pk_mul_f32 v[34:35], v[34:35], v[38:39]
	v_add_f32_e32 v33, 1.0, v33
	v_rcp_f32_e32 v42, v33
	v_mul_f32_e32 v33, 0xbfb8aa3b, v41
	v_exp_f32_e32 v33, v33
	v_cvt_pk_bf16_f32 v38, v34, v35
	v_pk_mul_f32 v[34:35], v[18:19], v[18:19]
	v_pk_mul_f32 v[18:19], v[94:95], v[18:19]
	v_add_f32_e32 v33, 1.0, v33
	v_rcp_f32_e32 v43, v33
	s_nop 0
	v_pk_mul_f32 v[40:41], v[42:43], v[40:41]
	s_nop 0
	v_pk_mul_f32 v[18:19], v[40:41], v[18:19]
	s_nop 0
	v_cvt_pk_bf16_f32 v39, v18, v19
	v_lshl_add_u64 v[18:19], v[36:37], 0, v[198:199]
	v_lshlrev_b32_e32 v36, 16, v126
	global_store_dwordx2 v[18:19], v[38:39], off
	v_pk_mul_f32 v[38:39], v[20:21], v[32:33] op_sel_hi:[1,0]
	v_mul_f32_e32 v33, 0xbfb8aa3b, v36
	v_exp_f32_e32 v33, v33
	v_and_b32_e32 v37, 0xffff0000, v126
	v_pk_mul_f32 v[20:21], v[38:39], v[38:39]
	v_pk_mul_f32 v[38:39], v[88:89], v[38:39]
	v_add_f32_e32 v33, 1.0, v33
	v_rcp_f32_e32 v40, v33
	v_mul_f32_e32 v33, 0xbfb8aa3b, v37
	v_exp_f32_e32 v33, v33
	v_add_f32_e32 v20, v20, v21
	v_add_f32_e32 v21, v34, v35
	v_add_f32_e32 v16, v16, v21
	v_add_f32_e32 v33, 1.0, v33
	v_rcp_f32_e32 v41, v33
	s_nop 0
	v_pk_mul_f32 v[36:37], v[40:41], v[36:37]
	s_nop 0
	v_pk_mul_f32 v[36:37], v[36:37], v[38:39]
	v_lshlrev_b32_e32 v38, 16, v127
	v_pk_mul_f32 v[40:41], v[22:23], v[32:33] op_sel_hi:[1,0]
	v_mul_f32_e32 v33, 0xbfb8aa3b, v38
	v_exp_f32_e32 v33, v33
	v_and_b32_e32 v39, 0xffff0000, v127
	v_pk_mul_f32 v[22:23], v[40:41], v[40:41]
	v_pk_mul_f32 v[40:41], v[90:91], v[40:41]
	v_add_f32_e32 v33, 1.0, v33
	v_rcp_f32_e32 v42, v33
	v_mul_f32_e32 v33, 0xbfb8aa3b, v39
	v_exp_f32_e32 v33, v33
	v_cvt_pk_bf16_f32 v36, v36, v37
	v_add_f32_e32 v22, v22, v23
	v_add_f32_e32 v20, v20, v22
	v_add_f32_e32 v33, 1.0, v33
	v_rcp_f32_e32 v43, v33
	v_add_f32_e32 v16, v16, v20
	v_pk_mul_f32 v[38:39], v[42:43], v[38:39]
	s_nop 0
	v_pk_mul_f32 v[38:39], v[38:39], v[40:41]
	s_nop 0
	v_cvt_pk_bf16_f32 v37, v38, v39
	global_store_dwordx2 v[18:19], v[36:37], off offset:16
	v_lshlrev_b32_e32 v36, 16, v124
	v_pk_mul_f32 v[38:39], v[24:25], v[32:33] op_sel_hi:[1,0]
	v_mul_f32_e32 v33, 0xbfb8aa3b, v36
	v_exp_f32_e32 v33, v33
	v_and_b32_e32 v37, 0xffff0000, v124
	v_pk_mul_f32 v[24:25], v[38:39], v[38:39]
	v_pk_mul_f32 v[38:39], v[84:85], v[38:39]
	v_add_f32_e32 v33, 1.0, v33
	v_rcp_f32_e32 v40, v33
	v_mul_f32_e32 v33, 0xbfb8aa3b, v37
	v_exp_f32_e32 v33, v33
	v_add_f32_e32 v24, v24, v25
	v_add_f32_e32 v33, 1.0, v33
	v_rcp_f32_e32 v41, v33
	s_nop 0
	v_pk_mul_f32 v[36:37], v[40:41], v[36:37]
	s_nop 0
	v_pk_mul_f32 v[36:37], v[36:37], v[38:39]
	v_lshlrev_b32_e32 v38, 16, v125
	v_pk_mul_f32 v[40:41], v[26:27], v[32:33] op_sel_hi:[1,0]
	v_mul_f32_e32 v33, 0xbfb8aa3b, v38
	v_exp_f32_e32 v33, v33
	v_and_b32_e32 v39, 0xffff0000, v125
	v_pk_mul_f32 v[26:27], v[40:41], v[40:41]
	v_pk_mul_f32 v[40:41], v[86:87], v[40:41]
	v_add_f32_e32 v33, 1.0, v33
	v_rcp_f32_e32 v42, v33
	v_mul_f32_e32 v33, 0xbfb8aa3b, v39
	v_exp_f32_e32 v33, v33
	v_cvt_pk_bf16_f32 v36, v36, v37
	v_add_f32_e32 v33, 1.0, v33
	v_rcp_f32_e32 v43, v33
	s_nop 0
	v_pk_mul_f32 v[38:39], v[42:43], v[38:39]
	s_nop 0
	v_pk_mul_f32 v[38:39], v[38:39], v[40:41]
	s_nop 0
	v_cvt_pk_bf16_f32 v37, v38, v39
	global_store_dwordx2 v[18:19], v[36:37], off offset:32
	v_lshlrev_b32_e32 v36, 16, v122
	v_pk_mul_f32 v[38:39], v[28:29], v[32:33] op_sel_hi:[1,0]
	v_mul_f32_e32 v33, 0xbfb8aa3b, v36
	v_exp_f32_e32 v33, v33
	v_and_b32_e32 v37, 0xffff0000, v122
	v_pk_mul_f32 v[28:29], v[38:39], v[38:39]
	v_pk_mul_f32 v[38:39], v[80:81], v[38:39]
	v_add_f32_e32 v33, 1.0, v33
	v_rcp_f32_e32 v40, v33
	v_mul_f32_e32 v33, 0xbfb8aa3b, v37
	v_exp_f32_e32 v33, v33
	v_add_f32_e32 v17, v28, v29
	v_add_f32_e32 v33, 1.0, v33
	v_rcp_f32_e32 v41, v33
	s_nop 0
	v_pk_mul_f32 v[36:37], v[40:41], v[36:37]
	s_nop 0
	v_pk_mul_f32 v[36:37], v[36:37], v[38:39]
	v_lshlrev_b32_e32 v38, 16, v123
	v_pk_mul_f32 v[40:41], v[30:31], v[32:33] op_sel_hi:[1,0]
	v_mul_f32_e32 v33, 0xbfb8aa3b, v38
	v_exp_f32_e32 v33, v33
	v_and_b32_e32 v39, 0xffff0000, v123
	v_pk_mul_f32 v[30:31], v[40:41], v[40:41]
	v_pk_mul_f32 v[40:41], v[82:83], v[40:41]
	v_add_f32_e32 v33, 1.0, v33
	v_rcp_f32_e32 v42, v33
	v_mul_f32_e32 v33, 0xbfb8aa3b, v39
	v_exp_f32_e32 v33, v33
	v_cvt_pk_bf16_f32 v36, v36, v37
	v_add_f32_e32 v33, 1.0, v33
	v_rcp_f32_e32 v43, v33
	s_nop 0
	v_pk_mul_f32 v[38:39], v[42:43], v[38:39]
	s_nop 0
	v_pk_mul_f32 v[38:39], v[38:39], v[40:41]
	s_nop 0
	v_cvt_pk_bf16_f32 v37, v38, v39
	global_store_dwordx2 v[18:19], v[36:37], off offset:48
	v_lshlrev_b32_e32 v36, 16, v120
	v_pk_mul_f32 v[38:39], v[0:1], v[32:33] op_sel_hi:[1,0]
	v_mul_f32_e32 v33, 0xbfb8aa3b, v36
	v_exp_f32_e32 v33, v33
	v_and_b32_e32 v37, 0xffff0000, v120
	v_pk_mul_f32 v[0:1], v[38:39], v[38:39]
	v_pk_mul_f32 v[38:39], v[76:77], v[38:39]
	v_add_f32_e32 v33, 1.0, v33
	v_rcp_f32_e32 v40, v33
	v_mul_f32_e32 v33, 0xbfb8aa3b, v37
	v_exp_f32_e32 v33, v33
	v_add_f32_e32 v0, v0, v1
	v_add_f32_e32 v33, 1.0, v33
	v_rcp_f32_e32 v41, v33
	s_nop 0
	v_pk_mul_f32 v[36:37], v[40:41], v[36:37]
	s_nop 0
	v_pk_mul_f32 v[36:37], v[36:37], v[38:39]
	v_lshlrev_b32_e32 v38, 16, v121
	v_pk_mul_f32 v[40:41], v[2:3], v[32:33] op_sel_hi:[1,0]
	v_mul_f32_e32 v33, 0xbfb8aa3b, v38
	v_exp_f32_e32 v33, v33
	v_and_b32_e32 v39, 0xffff0000, v121
	v_pk_mul_f32 v[2:3], v[40:41], v[40:41]
	v_pk_mul_f32 v[40:41], v[78:79], v[40:41]
	v_add_f32_e32 v33, 1.0, v33
	v_rcp_f32_e32 v42, v33
	v_mul_f32_e32 v33, 0xbfb8aa3b, v39
	v_exp_f32_e32 v33, v33
	v_cvt_pk_bf16_f32 v36, v36, v37
	v_add_f32_e32 v2, v2, v3
	v_add_f32_e32 v0, v0, v2
	v_add_f32_e32 v33, 1.0, v33
	v_rcp_f32_e32 v43, v33
	s_nop 0
	v_pk_mul_f32 v[38:39], v[42:43], v[38:39]
	s_nop 0
	v_pk_mul_f32 v[38:39], v[38:39], v[40:41]
	s_nop 0
	v_cvt_pk_bf16_f32 v37, v38, v39
	global_store_dwordx2 v[18:19], v[36:37], off offset:64
	v_lshlrev_b32_e32 v36, 16, v118
	v_pk_mul_f32 v[38:39], v[4:5], v[32:33] op_sel_hi:[1,0]
	v_mul_f32_e32 v33, 0xbfb8aa3b, v36
	v_exp_f32_e32 v33, v33
	v_and_b32_e32 v37, 0xffff0000, v118
	v_pk_mul_f32 v[4:5], v[38:39], v[38:39]
	v_pk_mul_f32 v[38:39], v[72:73], v[38:39]
	v_add_f32_e32 v33, 1.0, v33
	v_rcp_f32_e32 v40, v33
	v_mul_f32_e32 v33, 0xbfb8aa3b, v37
	v_exp_f32_e32 v33, v33
	v_add_f32_e32 v2, v4, v5
	v_add_f32_e32 v33, 1.0, v33
	v_rcp_f32_e32 v41, v33
	s_nop 0
	v_pk_mul_f32 v[36:37], v[40:41], v[36:37]
	s_nop 0
	v_pk_mul_f32 v[36:37], v[36:37], v[38:39]
	v_lshlrev_b32_e32 v38, 16, v119
	v_pk_mul_f32 v[40:41], v[6:7], v[32:33] op_sel_hi:[1,0]
	v_mul_f32_e32 v33, 0xbfb8aa3b, v38
	v_exp_f32_e32 v33, v33
	v_and_b32_e32 v39, 0xffff0000, v119
	v_pk_mul_f32 v[6:7], v[40:41], v[40:41]
	v_pk_mul_f32 v[40:41], v[74:75], v[40:41]
	v_add_f32_e32 v33, 1.0, v33
	v_rcp_f32_e32 v42, v33
	v_mul_f32_e32 v33, 0xbfb8aa3b, v39
	v_exp_f32_e32 v33, v33
	v_cvt_pk_bf16_f32 v36, v36, v37
	v_add_f32_e32 v1, v6, v7
	v_add_f32_e32 v1, v2, v1
	v_add_f32_e32 v33, 1.0, v33
	v_rcp_f32_e32 v43, v33
	v_pk_mul_f32 v[8:9], v[8:9], v[32:33] op_sel_hi:[1,0]
	v_pk_mul_f32 v[38:39], v[42:43], v[38:39]
	s_nop 0
	v_pk_mul_f32 v[38:39], v[38:39], v[40:41]
	s_nop 0
	v_cvt_pk_bf16_f32 v37, v38, v39
	global_store_dwordx2 v[18:19], v[36:37], off offset:80
	v_lshlrev_b32_e32 v36, 16, v116
	v_mul_f32_e32 v33, 0xbfb8aa3b, v36
	v_exp_f32_e32 v33, v33
	v_and_b32_e32 v37, 0xffff0000, v116
	v_pk_mul_f32 v[38:39], v[8:9], v[8:9]
	v_pk_mul_f32 v[8:9], v[68:69], v[8:9]
	v_add_f32_e32 v33, 1.0, v33
	v_rcp_f32_e32 v40, v33
	v_mul_f32_e32 v33, 0xbfb8aa3b, v37
	v_exp_f32_e32 v33, v33
	v_add_f32_e32 v2, v38, v39
	v_add_f32_e32 v33, 1.0, v33
	v_rcp_f32_e32 v41, v33
	v_pk_mul_f32 v[10:11], v[10:11], v[32:33] op_sel_hi:[1,0]
	v_pk_mul_f32 v[36:37], v[40:41], v[36:37]
	s_nop 0
	v_pk_mul_f32 v[8:9], v[36:37], v[8:9]
	v_lshlrev_b32_e32 v36, 16, v117
	v_cvt_pk_bf16_f32 v8, v8, v9
	v_mul_f32_e32 v9, 0xbfb8aa3b, v36
	v_exp_f32_e32 v9, v9
	v_and_b32_e32 v37, 0xffff0000, v117
	v_pk_mul_f32 v[40:41], v[10:11], v[10:11]
	v_pk_mul_f32 v[10:11], v[70:71], v[10:11]
	v_add_f32_e32 v9, 1.0, v9
	v_rcp_f32_e32 v42, v9
	v_mul_f32_e32 v9, 0xbfb8aa3b, v37
	v_exp_f32_e32 v9, v9
	s_nop 0
	v_add_f32_e32 v9, 1.0, v9
	v_rcp_f32_e32 v43, v9
	s_nop 0
	v_pk_mul_f32 v[36:37], v[42:43], v[36:37]
	s_nop 0
	v_pk_mul_f32 v[10:11], v[36:37], v[10:11]
	s_nop 0
	v_cvt_pk_bf16_f32 v9, v10, v11
	global_store_dwordx2 v[18:19], v[8:9], off offset:96
	v_lshlrev_b32_e32 v8, 16, v114
	v_pk_mul_f32 v[10:11], v[12:13], v[32:33] op_sel_hi:[1,0]
	v_mul_f32_e32 v33, 0xbfb8aa3b, v8
	v_exp_f32_e32 v33, v33
	v_and_b32_e32 v9, 0xffff0000, v114
	v_pk_mul_f32 v[12:13], v[10:11], v[10:11]
	v_pk_mul_f32 v[10:11], v[64:65], v[10:11]
	v_add_f32_e32 v33, 1.0, v33
	v_rcp_f32_e32 v36, v33
	v_mul_f32_e32 v33, 0xbfb8aa3b, v9
	v_exp_f32_e32 v33, v33
	s_nop 0
	v_add_f32_e32 v33, 1.0, v33
	v_rcp_f32_e32 v37, v33
	v_pk_mul_f32 v[14:15], v[14:15], v[32:33] op_sel_hi:[1,0]
	v_pk_mul_f32 v[8:9], v[36:37], v[8:9]
	s_nop 0
	v_pk_mul_f32 v[8:9], v[8:9], v[10:11]
	v_pk_mul_f32 v[32:33], v[14:15], v[14:15]
	v_cvt_pk_bf16_f32 v8, v8, v9
	v_add_f32_e32 v9, v26, v27
	v_add_f32_e32 v9, v24, v9
	v_add_f32_e32 v9, v9, v16
	v_add_f32_e32 v16, v30, v31
	v_add_f32_e32 v16, v17, v16
	v_add_f32_e32 v9, v16, v9
	v_add_f32_e32 v0, v0, v9
	v_add_f32_e32 v0, v1, v0
	v_add_f32_e32 v1, v40, v41
	v_add_f32_e32 v1, v2, v1
	v_add_f32_e32 v0, v1, v0
	v_add_f32_e32 v1, v32, v33
	v_add_f32_e32 v2, v12, v13
	v_lshlrev_b32_e32 v10, 16, v115
	v_add_f32_e32 v1, v2, v1
	v_add_f32_e32 v0, v1, v0
	v_mul_f32_e32 v1, 0xbfb8aa3b, v10
	v_exp_f32_e32 v1, v1
	v_and_b32_e32 v11, 0xffff0000, v115
	v_pk_mul_f32 v[4:5], v[66:67], v[14:15]
	v_add_f32_e32 v1, 1.0, v1
	v_rcp_f32_e32 v2, v1
	v_mul_f32_e32 v1, 0xbfb8aa3b, v11
	v_exp_f32_e32 v1, v1
	s_nop 0
	v_add_f32_e32 v1, 1.0, v1
	v_rcp_f32_e32 v3, v1
	ds_bpermute_b32 v1, v133, v0
	v_pk_mul_f32 v[2:3], v[2:3], v[10:11]
	s_nop 0
	v_pk_mul_f32 v[2:3], v[2:3], v[4:5]
	s_nop 0
	v_cvt_pk_bf16_f32 v9, v2, v3
	global_store_dwordx2 v[18:19], v[8:9], off offset:112
	s_and_saveexec_b64 s[0:1], vcc
	s_cbranch_execz .LBB0_443
	s_add_u32 s4, s28, s4
	s_addc_u32 s5, s29, s5
	s_waitcnt lgkmcnt(0)
	v_add_f32_e32 v2, v0, v1
	v_lshlrev_b64 v[0:1], 5, v[112:113]
	v_lshl_add_u64 v[0:1], s[4:5], 0, v[0:1]
	v_lshlrev_b32_e32 v198, 2, v129
	v_lshl_add_u64 v[0:1], v[0:1], 0, v[198:199]
	global_store_dword v[0:1], v2, off

.LBB0_460:
	s_or_b64 exec, exec, s[0:1]
	s_lshl_b32 s0, s86, 17
	v_readlane_b32 s1, v254, 54
	s_or_b32 s0, s0, s1
	s_add_u32 s1, s28, s54
	s_addc_u32 s4, s29, s55
	s_add_u32 s0, s1, s0
	s_waitcnt vmcnt(0)
	v_lshlrev_b32_e32 v0, 3, v21
	s_addc_u32 s1, s4, 0
	v_and_b32_e32 v4, 0xffffff80, v0
	v_lshl_add_u64 v[2:3], s[0:1], 0, v[198:199]
	v_ashrrev_i32_e32 v5, 31, v4
	v_lshl_add_u64 v[6:7], v[4:5], 1, v[2:3]
	v_add_u32_e32 v8, 0x1000, v4
	v_add_u32_e32 v10, 0x2000, v4
	v_add_u32_e32 v4, 0x3000, v4
	v_ashrrev_i32_e32 v9, 31, v8
	v_ashrrev_i32_e32 v11, 31, v10
	v_ashrrev_i32_e32 v5, 31, v4
	v_lshl_add_u64 v[8:9], v[8:9], 1, v[2:3]
	v_lshl_add_u64 v[10:11], v[10:11], 1, v[2:3]
	v_lshl_add_u64 v[12:13], v[4:5], 1, v[2:3]
	global_load_dwordx4 v[2:5], v[6:7], off
	global_load_dwordx4 v[32:35], v[8:9], off
	global_load_dwordx4 v[36:39], v[10:11], off
	global_load_dwordx4 v[40:43], v[12:13], off
	v_mad_u64_u32 v[14:15], s[0:1], v22, s66, v[20:21]
	v_mad_u64_u32 v[6:7], s[0:1], v23, s66, v[20:21]
	v_lshrrev_b32_e32 v0, 1, v21
	v_and_b32_e32 v1, 31, v132
	v_ashrrev_i32_e32 v96, 8, v21
	v_and_b32_e32 v119, 0x60, v0
	v_readlane_b32 s36, v254, 0
	v_lshlrev_b32_e32 v123, 6, v96
	v_readlane_b32 s48, v254, 12
	v_readlane_b32 s49, v254, 13
	v_bfe_u32 v97, v132, 5, 1
	v_readlane_b32 s40, v254, 4
	v_readlane_b32 s41, v254, 5
	s_mov_b64 s[12:13], s[48:49]
	v_readlane_b32 s42, v254, 6
	v_readlane_b32 s43, v254, 7
	v_readlane_b32 s44, v254, 8
	v_readlane_b32 s45, v254, 9
	s_mov_b64 s[4:5], s[40:41]
	s_mov_b64 s[8:9], s[44:45]
	v_ashrrev_i32_e32 v135, 2, v21
	v_and_b32_e32 v134, -16, v135
	v_mul_lo_u32 v133, v134, s66
	v_readlane_b32 s37, v254, 1
	v_readlane_b32 s38, v254, 2
	v_readlane_b32 s39, v254, 3
	v_readlane_b32 s46, v254, 10
	v_readlane_b32 s47, v254, 11
	v_readlane_b32 s50, v254, 14
	v_readlane_b32 s51, v254, 15
	s_mov_b64 s[6:7], s[42:43]
	s_waitcnt vmcnt(3)
	ds_write_b128 v14, v[2:5] offset:39168
	s_waitcnt vmcnt(2)
	ds_write_b128 v6, v[32:35] offset:39168
	v_mad_u64_u32 v[6:7], s[0:1], v24, s66, v[20:21]
	s_waitcnt vmcnt(1)
	ds_write_b128 v6, v[36:39] offset:39168
	v_mad_u64_u32 v[6:7], s[0:1], v25, s66, v[20:21]
	v_readlane_b32 s0, v255, 1
	s_waitcnt vmcnt(0)
	ds_write_b128 v6, v[40:43] offset:39168
	v_or3_b32 v198, v1, s0, v119
	v_readlane_b32 s0, v254, 57
	v_mov_b64_e32 v[2:3], s[52:53]
	s_nop 0
	v_add_u32_e32 v0, s0, v123
	v_mad_u64_u32 v[2:3], s[0:1], v198, s62, v[2:3]
	v_lshl_or_b32 v112, v97, 2, v0
	s_add_u32 s0, s12, s88
	s_addc_u32 s1, s13, s89
	v_ashrrev_i32_e32 v113, 31, v112
	s_add_u32 s4, s8, s88
	v_lshlrev_b64 v[4:5], 2, v[112:113]
	s_addc_u32 s5, s9, s89
	v_lshl_add_u64 v[2:3], v[112:113], 1, v[2:3]
	v_lshl_add_u64 v[6:7], s[0:1], 0, v[4:5]
	global_load_dwordx2 v[114:115], v[2:3], off offset:3584
	v_lshl_add_u64 v[4:5], s[4:5], 0, v[4:5]
	global_load_dwordx4 v[92:95], v[6:7], off
	global_load_dwordx4 v[88:91], v[4:5], off
	global_load_dwordx2 v[110:111], v[2:3], off offset:3600
	global_load_dwordx4 v[84:87], v[6:7], off offset:32
	global_load_dwordx4 v[80:83], v[4:5], off offset:32
	global_load_dwordx2 v[108:109], v[2:3], off offset:3616
	global_load_dwordx4 v[76:79], v[6:7], off offset:64
	global_load_dwordx4 v[72:75], v[4:5], off offset:64
	global_load_dwordx2 v[106:107], v[2:3], off offset:3632
	global_load_dwordx4 v[68:71], v[6:7], off offset:96
	global_load_dwordx4 v[64:67], v[4:5], off offset:96
	global_load_dwordx2 v[104:105], v[2:3], off offset:3648
	global_load_dwordx4 v[60:63], v[6:7], off offset:128
	global_load_dwordx4 v[56:59], v[4:5], off offset:128
	global_load_dwordx2 v[102:103], v[2:3], off offset:3664
	global_load_dwordx4 v[52:55], v[6:7], off offset:160
	global_load_dwordx4 v[48:51], v[4:5], off offset:160
	global_load_dwordx2 v[100:101], v[2:3], off offset:3680
	global_load_dwordx4 v[44:47], v[6:7], off offset:192
	global_load_dwordx4 v[40:43], v[4:5], off offset:192
	global_load_dwordx2 v[98:99], v[2:3], off offset:3696
	global_load_dwordx4 v[36:39], v[6:7], off offset:224
	global_load_dwordx4 v[32:35], v[4:5], off offset:224
	s_cmp_lt_i32 s96, 2
	s_waitcnt lgkmcnt(0)
	s_barrier
	s_cbranch_scc1 .LBB0_470
	s_cmp_gt_i32 s96, 2
	s_mov_b64 s[0:1], -1
	s_cbranch_scc0 .LBB0_463
	v_lshlrev_b32_e32 v0, 2, v132
	v_and_b32_e32 v129, 0xfc, v0
	v_add_u32_e32 v137, v133, v129
	ds_read2_b32 v[2:3], v137 offset1:68
	ds_read2_b32 v[4:5], v137 offset0:136 offset1:204
	v_readlane_b32 s1, v255, 3
	v_or_b32_e32 v122, 1, v134
	v_readlane_b32 s0, v255, 0
	v_add_u32_e32 v124, s1, v122
	v_max_i32_e32 v125, 8, v124
	v_or_b32_e32 v124, 8, v124
	v_add_u32_e32 v0, 0x400, v137
	v_min_i32_e32 v124, s0, v124
	s_waitcnt lgkmcnt(1)
	v_lshlrev_b32_e32 v28, 16, v2
	v_and_b32_e32 v29, 0xffff0000, v2
	v_lshlrev_b32_e32 v26, 16, v3
	v_and_b32_e32 v27, 0xffff0000, v3
	ds_read2_b32 v[2:3], v0 offset0:16 offset1:84
	v_sub_u32_e32 v124, v124, v125
	v_add_u32_e32 v124, 8, v124
	v_cvt_f32_i32_e32 v126, v124
	s_waitcnt lgkmcnt(1)
	v_lshlrev_b32_e32 v24, 16, v4
	v_and_b32_e32 v25, 0xffff0000, v4
	v_lshlrev_b32_e32 v22, 16, v5
	v_and_b32_e32 v23, 0xffff0000, v5
	ds_read2_b32 v[4:5], v0 offset0:152 offset1:220
	v_add_u32_e32 v0, 0x800, v137
	s_waitcnt lgkmcnt(1)
	v_lshlrev_b32_e32 v30, 16, v2
	v_and_b32_e32 v31, 0xffff0000, v2
	v_lshlrev_b32_e32 v20, 16, v3
	v_and_b32_e32 v21, 0xffff0000, v3
	ds_read2_b32 v[2:3], v0 offset0:32 offset1:100
	v_add_u32_e32 v141, s1, v134
	v_mul_lo_u32 v140, v122, s66
	v_rcp_iflag_f32_e32 v122, v126
	v_add_u32_e32 v126, 2, v141
	v_add_u32_e32 v169, 10, v141
	v_add_u32_e32 v130, 3, v141
	v_add_u32_e32 v173, 11, v141
	v_max_i32_e32 v126, 8, v126
	v_min_i32_e32 v127, s0, v169
	v_max_i32_e32 v130, 8, v130
	v_min_i32_e32 v131, s0, v173
	v_sub_u32_e32 v126, v127, v126
	v_sub_u32_e32 v130, v131, v130
	s_waitcnt lgkmcnt(1)
	v_lshlrev_b32_e32 v18, 16, v4
	v_and_b32_e32 v19, 0xffff0000, v4
	v_lshlrev_b32_e32 v16, 16, v5
	v_and_b32_e32 v17, 0xffff0000, v5
	ds_read2_b32 v[4:5], v0 offset0:168 offset1:236
	v_add_u32_e32 v0, 0xc00, v137
	v_add_u32_e32 v126, 8, v126
	v_add_u32_e32 v130, 8, v130
	s_waitcnt lgkmcnt(1)
	v_lshlrev_b32_e32 v14, 16, v2
	v_and_b32_e32 v15, 0xffff0000, v2
	v_lshlrev_b32_e32 v12, 16, v3
	v_and_b32_e32 v13, 0xffff0000, v3
	ds_read2_b32 v[2:3], v0 offset0:48 offset1:116
	ds_read2_b32 v[116:117], v0 offset0:184 offset1:252
	v_cvt_f32_i32_e32 v128, v126
	v_cvt_f32_i32_e32 v138, v130
	v_add_u32_e32 v181, 12, v141
	s_waitcnt lgkmcnt(2)
	v_lshlrev_b32_e32 v10, 16, v4
	v_rcp_iflag_f32_e32 v136, v128
	v_rcp_iflag_f32_e32 v128, v138
	v_add_u32_e32 v138, 4, v141
	v_and_b32_e32 v11, 0xffff0000, v4
	v_lshlrev_b32_e32 v8, 16, v5
	v_and_b32_e32 v9, 0xffff0000, v5
	s_waitcnt lgkmcnt(1)
	v_lshlrev_b32_e32 v6, 16, v2
	v_and_b32_e32 v7, 0xffff0000, v2
	v_lshlrev_b32_e32 v4, 16, v3
	v_and_b32_e32 v5, 0xffff0000, v3
	s_waitcnt lgkmcnt(0)
	v_lshlrev_b32_e32 v2, 16, v116
	v_and_b32_e32 v3, 0xffff0000, v116
	v_or_b32_e32 v116, 8, v141
	v_max_i32_e32 v138, 8, v138
	v_min_i32_e32 v139, s0, v181
	v_max_i32_e32 v0, 8, v141
	v_min_i32_e32 v116, s0, v116
	v_sub_u32_e32 v138, v139, v138
	v_sub_u32_e32 v0, v116, v0
	v_add_u32_e32 v138, 8, v138
	v_add_u32_e32 v0, 8, v0
	v_cvt_f32_i32_e32 v142, v138
	v_add_u32_e32 v138, 0x1400, v137
	v_cvt_f32_i32_e32 v118, v0
	v_or_b32_e32 v0, 0x12100, v129
	ds_read2_b32 v[138:139], v138 offset0:80 offset1:148
	v_add_u32_e32 v144, 0x330, v140
	v_add_u32_e32 v185, v0, v144
	v_add_u32_e32 v194, v144, v129
	v_add_u32_e32 v144, 6, v141
	v_add_u32_e32 v195, 14, v141
	v_max_i32_e32 v146, 8, v144
	v_min_i32_e32 v147, s0, v195
	v_sub_u32_e32 v146, v147, v146
	v_add_u32_e32 v146, 8, v146
	v_cvt_f32_i32_e32 v148, v146
	s_waitcnt lgkmcnt(0)
	v_lshlrev_b32_e32 v146, 16, v139
	v_and_b32_e32 v147, 0xffff0000, v139
	v_add_u32_e32 v139, 0x1600, v137
	ds_read2_b32 v[152:153], v139 offset0:88 offset1:156
	v_add_u32_e32 v139, 7, v141
	v_add_u32_e32 v151, 15, v141
	v_add_u32_e32 v161, v0, v140
	v_rcp_iflag_f32_e32 v140, v142
	v_lshlrev_b32_e32 v142, 16, v138
	v_and_b32_e32 v143, 0xffff0000, v138
	v_add_u32_e32 v138, 5, v141
	v_add_u32_e32 v187, 13, v141
	v_max_i32_e32 v139, 8, v139
	v_min_i32_e32 v151, s0, v151
	v_max_i32_e32 v138, 8, v138
	v_min_i32_e32 v145, s0, v187
	v_add_u32_e32 v144, 0x800, v194
	v_sub_u32_e32 v139, v151, v139
	v_sub_u32_e32 v138, v145, v138
	ds_read2_b32 v[144:145], v144 offset0:168 offset1:236
	v_add_u32_e32 v139, 8, v139
	v_cvt_f32_i32_e32 v139, v139
	s_waitcnt lgkmcnt(1)
	v_lshlrev_b32_e32 v154, 16, v152
	v_and_b32_e32 v155, 0xffff0000, v152
	s_waitcnt lgkmcnt(0)
	v_lshlrev_b32_e32 v150, 16, v144
	v_and_b32_e32 v151, 0xffff0000, v144
	v_rcp_iflag_f32_e32 v144, v139
	v_add_u32_e32 v139, 8, v141
	v_add_u32_e32 v152, 16, v141
	v_max_i32_e32 v139, 8, v139
	v_min_i32_e32 v152, s0, v152
	v_sub_u32_e32 v139, v152, v139
	v_add_u32_e32 v139, 8, v139
	v_cvt_f32_i32_e32 v139, v139
	v_lshlrev_b32_e32 v156, 16, v145
	v_and_b32_e32 v157, 0xffff0000, v145
	v_add_u32_e32 v145, 17, v141
	v_rcp_iflag_f32_e32 v160, v139
	v_add_u32_e32 v139, 0x1800, v137
	ds_read2_b32 v[164:165], v139 offset0:96 offset1:164
	v_add_u32_e32 v139, 9, v141
	v_max_i32_e32 v139, 8, v139
	v_min_i32_e32 v145, s0, v145
	v_add_u32_e32 v170, 0xc00, v194
	v_sub_u32_e32 v139, v145, v139
	ds_read2_b32 v[158:159], v170 offset0:48 offset1:116
	v_add_u32_e32 v139, 8, v139
	v_cvt_f32_i32_e32 v139, v139
	v_add_u32_e32 v145, 18, v141
	v_min_i32_e32 v145, s0, v145
	s_waitcnt lgkmcnt(0)
	v_lshlrev_b32_e32 v162, 16, v158
	v_and_b32_e32 v163, 0xffff0000, v158
	v_rcp_iflag_f32_e32 v158, v139
	v_max_i32_e32 v139, 8, v169
	v_sub_u32_e32 v139, v145, v139
	v_add_u32_e32 v139, 8, v139
	v_cvt_f32_i32_e32 v139, v139
	v_add_u32_e32 v145, 19, v141
	v_min_i32_e32 v145, s0, v145
	ds_read2_b32 v[170:171], v170 offset0:184 offset1:252
	v_rcp_iflag_f32_e32 v172, v139
	v_add_u32_e32 v139, 0x1a00, v137
	ds_read2_b32 v[176:177], v139 offset0:104 offset1:172
	v_max_i32_e32 v139, 8, v173
	v_sub_u32_e32 v139, v145, v139
	v_add_u32_e32 v139, 8, v139
	v_cvt_f32_i32_e32 v139, v139
	v_pk_add_f32 v[204:205], v[28:29], 0 op_sel_hi:[1,0]
	v_add_u32_e32 v145, 20, v141
	v_pk_add_f32 v[204:205], v[204:205], v[26:27]
	s_waitcnt lgkmcnt(1)
	v_lshlrev_b32_e32 v174, 16, v170
	v_pk_add_f32 v[204:205], v[204:205], v[24:25]
	v_and_b32_e32 v175, 0xffff0000, v170
	v_pk_add_f32 v[204:205], v[204:205], v[22:23]
	v_rcp_iflag_f32_e32 v170, v139
	v_max_i32_e32 v139, 8, v181
	v_min_i32_e32 v145, s0, v145
	v_pk_add_f32 v[204:205], v[204:205], v[30:31]
	v_sub_u32_e32 v139, v145, v139
	v_pk_add_f32 v[204:205], v[204:205], v[20:21]
	v_add_u32_e32 v139, 8, v139
	v_pk_add_f32 v[30:31], v[142:143], v[30:31] neg_lo:[0,1] neg_hi:[0,1]
	v_pk_add_f32 v[142:143], v[204:205], v[18:19]
	v_cvt_f32_i32_e32 v139, v139
	v_pk_add_f32 v[142:143], v[142:143], v[16:17]
	v_add_u32_e32 v120, 0x1000, v137
	v_pk_add_f32 v[142:143], v[142:143], v[14:15]
	ds_read2_b32 v[120:121], v120 offset0:64 offset1:132
	v_pk_add_f32 v[142:143], v[142:143], v[12:13]
	v_add_u32_e32 v126, 0x1200, v137
	v_pk_add_f32 v[142:143], v[142:143], v[10:11]
	ds_read2_b32 v[126:127], v126 offset0:72 offset1:140
	v_rcp_iflag_f32_e32 v184, v139
	v_add_u32_e32 v139, 0x1c00, v137
	v_add_u32_e32 v145, 21, v141
	v_pk_add_f32 v[142:143], v[142:143], v[8:9]
	ds_read2_b32 v[188:189], v139 offset0:112 offset1:180
	v_max_i32_e32 v139, 8, v187
	v_min_i32_e32 v145, s0, v145
	v_pk_add_f32 v[142:143], v[142:143], v[6:7]
	v_lshlrev_b32_e32 v168, 16, v159
	v_and_b32_e32 v169, 0xffff0000, v159
	v_add_u32_e32 v159, 0x1000, v194
	v_sub_u32_e32 v139, v145, v139
	v_pk_add_f32 v[142:143], v[142:143], v[4:5]
	v_lshlrev_b32_e32 v116, 16, v117
	v_and_b32_e32 v117, 0xffff0000, v117
	s_waitcnt lgkmcnt(2)
	v_lshlrev_b32_e32 v124, 16, v120
	v_and_b32_e32 v125, 0xffff0000, v120
	ds_read2_b32 v[182:183], v159 offset0:64 offset1:132
	v_add_u32_e32 v139, 8, v139
	v_pk_add_f32 v[142:143], v[142:143], v[2:3]
	v_lshlrev_b32_e32 v120, 16, v121
	v_and_b32_e32 v121, 0xffff0000, v121
	v_cvt_f32_i32_e32 v139, v139
	ds_read_b32 v137, v137 offset:8160
	v_pk_add_f32 v[116:117], v[142:143], v[116:117]
	v_pk_add_f32 v[28:29], v[124:125], v[28:29] neg_lo:[0,1] neg_hi:[0,1]
	v_rcp_iflag_f32_e32 v118, v118
	s_waitcnt lgkmcnt(3)
	v_lshlrev_b32_e32 v130, 16, v126
	v_and_b32_e32 v131, 0xffff0000, v126
	v_pk_add_f32 v[28:29], v[116:117], v[28:29]
	v_pk_add_f32 v[26:27], v[120:121], v[26:27] neg_lo:[0,1] neg_hi:[0,1]
	v_lshlrev_b32_e32 v126, 16, v127
	v_and_b32_e32 v127, 0xffff0000, v127
	v_pk_add_f32 v[26:27], v[28:29], v[26:27]
	v_pk_add_f32 v[24:25], v[130:131], v[24:25] neg_lo:[0,1] neg_hi:[0,1]
	v_add_u32_e32 v141, 22, v141
	v_pk_add_f32 v[24:25], v[26:27], v[24:25]
	v_pk_add_f32 v[22:23], v[126:127], v[22:23] neg_lo:[0,1] neg_hi:[0,1]
	v_add_u32_e32 v138, 8, v138
	s_waitcnt lgkmcnt(1)
	v_lshlrev_b32_e32 v186, 16, v182
	v_and_b32_e32 v187, 0xffff0000, v182
	v_rcp_iflag_f32_e32 v182, v139
	v_max_i32_e32 v139, 8, v195
	v_min_i32_e32 v141, s0, v141
	v_pk_add_f32 v[22:23], v[24:25], v[22:23]
	v_cvt_f32_i32_e32 v138, v138
	v_sub_u32_e32 v139, v141, v139
	v_pk_fma_f32 v[142:143], v[118:119], v[116:117], v[14:15] op_sel_hi:[0,1,1] neg_lo:[0,0,1] neg_hi:[0,0,1]
	v_pk_fma_f32 v[116:117], v[122:123], v[28:29], v[12:13] op_sel_hi:[0,1,1] neg_lo:[0,0,1] neg_hi:[0,0,1]
	s_waitcnt lgkmcnt(0)
	v_pk_fma_f32 v[28:29], v[136:137], v[26:27], v[10:11] op_sel_hi:[0,1,1] neg_lo:[0,0,1] neg_hi:[0,0,1]
	v_pk_fma_f32 v[26:27], v[128:129], v[24:25], v[8:9] op_sel_hi:[0,1,1] neg_lo:[0,0,1] neg_hi:[0,0,1]
	v_pk_fma_f32 v[24:25], v[140:141], v[22:23], v[6:7] op_sel_hi:[0,1,1] neg_lo:[0,0,1] neg_hi:[0,0,1]
	v_pk_add_f32 v[22:23], v[22:23], v[30:31]
	v_pk_add_f32 v[20:21], v[146:147], v[20:21] neg_lo:[0,1] neg_hi:[0,1]
	v_lshlrev_b32_e32 v152, 16, v153
	v_and_b32_e32 v153, 0xffff0000, v153
	v_add_u32_e32 v139, 8, v139
	v_pk_add_f32 v[20:21], v[22:23], v[20:21]
	v_pk_add_f32 v[18:19], v[154:155], v[18:19] neg_lo:[0,1] neg_hi:[0,1]
	v_lshlrev_b32_e32 v166, 16, v164
	v_and_b32_e32 v167, 0xffff0000, v164
	v_cvt_f32_i32_e32 v139, v139
	v_pk_add_f32 v[18:19], v[20:21], v[18:19]
	v_pk_add_f32 v[16:17], v[152:153], v[16:17] neg_lo:[0,1] neg_hi:[0,1]
	v_lshlrev_b32_e32 v164, 16, v165
	v_and_b32_e32 v165, 0xffff0000, v165
	ds_read_b32 v145, v194 offset:4896
	v_pk_add_f32 v[16:17], v[18:19], v[16:17]
	v_pk_add_f32 v[14:15], v[166:167], v[14:15] neg_lo:[0,1] neg_hi:[0,1]
	v_rcp_iflag_f32_e32 v138, v138
	v_rcp_iflag_f32_e32 v148, v148
	v_lshlrev_b32_e32 v178, 16, v176
	v_and_b32_e32 v179, 0xffff0000, v176
	v_pk_add_f32 v[14:15], v[16:17], v[14:15]
	v_pk_add_f32 v[12:13], v[164:165], v[12:13] neg_lo:[0,1] neg_hi:[0,1]
	v_lshlrev_b32_e32 v176, 16, v177
	v_and_b32_e32 v177, 0xffff0000, v177
	v_pk_add_f32 v[12:13], v[14:15], v[12:13]
	v_pk_add_f32 v[10:11], v[178:179], v[10:11] neg_lo:[0,1] neg_hi:[0,1]
	v_lshlrev_b32_e32 v190, 16, v188
	v_and_b32_e32 v191, 0xffff0000, v188
	v_rcp_iflag_f32_e32 v194, v139
	v_pk_add_f32 v[10:11], v[12:13], v[10:11]
	v_pk_add_f32 v[8:9], v[176:177], v[8:9] neg_lo:[0,1] neg_hi:[0,1]
	v_add_u32_e32 v149, v0, v133
	v_lshlrev_b32_e32 v188, 16, v189
	v_and_b32_e32 v189, 0xffff0000, v189
	v_cvt_pk_bf16_f32 v26, v26, v27
	v_pk_add_f32 v[8:9], v[10:11], v[8:9]
	v_pk_add_f32 v[6:7], v[190:191], v[6:7] neg_lo:[0,1] neg_hi:[0,1]
	ds_write_b32 v161, v26 offset:544
	v_cvt_pk_bf16_f32 v26, v24, v25
	v_pk_fma_f32 v[24:25], v[138:139], v[22:23], v[4:5] op_sel_hi:[0,1,1] neg_lo:[0,0,1] neg_hi:[0,0,1]
	v_pk_fma_f32 v[22:23], v[148:149], v[20:21], v[150:151] op_sel_hi:[0,1,1] neg_lo:[0,0,1] neg_hi:[0,0,1]
	s_waitcnt lgkmcnt(1)
	v_pk_fma_f32 v[20:21], v[144:145], v[18:19], v[156:157] op_sel_hi:[0,1,1] neg_lo:[0,0,1] neg_hi:[0,0,1]
	v_pk_add_f32 v[6:7], v[8:9], v[6:7]
	v_pk_add_f32 v[4:5], v[188:189], v[4:5] neg_lo:[0,1] neg_hi:[0,1]
	v_lshlrev_b32_e32 v180, 16, v171
	v_and_b32_e32 v181, 0xffff0000, v171
	v_lshlrev_b32_e32 v192, 16, v183
	v_and_b32_e32 v193, 0xffff0000, v183
	v_lshlrev_b32_e32 v200, 16, v145
	v_and_b32_e32 v201, 0xffff0000, v145
	v_and_b32_e32 v203, 0xffff0000, v137
	v_lshlrev_b32_e32 v202, 16, v137
	v_cvt_pk_bf16_f32 v118, v142, v143
	v_cvt_pk_bf16_f32 v116, v116, v117
	v_cvt_pk_bf16_f32 v28, v28, v29
	v_cvt_pk_bf16_f32 v24, v24, v25
	v_cvt_pk_bf16_f32 v22, v22, v23
	v_cvt_pk_bf16_f32 v20, v20, v21
	v_pk_add_f32 v[4:5], v[6:7], v[4:5]
	ds_write_b32 v149, v118
	ds_write2_b32 v161, v116, v28 offset1:68
	ds_write2_b32 v185, v26, v24 offset1:68
	ds_write2_b32 v185, v22, v20 offset0:136 offset1:204
	v_pk_fma_f32 v[18:19], v[160:161], v[16:17], v[162:163] op_sel_hi:[0,1,1] neg_lo:[0,0,1] neg_hi:[0,0,1]
	v_pk_fma_f32 v[16:17], v[158:159], v[14:15], v[168:169] op_sel_hi:[0,1,1] neg_lo:[0,0,1] neg_hi:[0,0,1]
	v_pk_fma_f32 v[14:15], v[172:173], v[12:13], v[174:175] op_sel_hi:[0,1,1] neg_lo:[0,0,1] neg_hi:[0,0,1]
	v_pk_fma_f32 v[12:13], v[170:171], v[10:11], v[180:181] op_sel_hi:[0,1,1] neg_lo:[0,0,1] neg_hi:[0,0,1]
	v_pk_fma_f32 v[10:11], v[184:185], v[8:9], v[186:187] op_sel_hi:[0,1,1] neg_lo:[0,0,1] neg_hi:[0,0,1]
	v_pk_fma_f32 v[8:9], v[182:183], v[6:7], v[192:193] op_sel_hi:[0,1,1] neg_lo:[0,0,1] neg_hi:[0,0,1]
	v_pk_fma_f32 v[6:7], v[194:195], v[4:5], v[200:201] op_sel_hi:[0,1,1] neg_lo:[0,0,1] neg_hi:[0,0,1]
	v_pk_add_f32 v[2:3], v[202:203], v[2:3] neg_lo:[0,1] neg_hi:[0,1]
	v_or_b32_e32 v22, 15, v135
	v_cvt_pk_bf16_f32 v18, v18, v19
	v_cvt_pk_bf16_f32 v16, v16, v17
	v_add_u32_e32 v17, 0x400, v185
	v_cvt_pk_bf16_f32 v14, v14, v15
	v_cvt_pk_bf16_f32 v12, v12, v13
	v_cvt_pk_bf16_f32 v10, v10, v11
	v_cvt_pk_bf16_f32 v8, v8, v9
	v_add_u32_e32 v9, 0x800, v185
	v_cvt_pk_bf16_f32 v6, v6, v7
	v_pk_add_f32 v[2:3], v[4:5], v[2:3]
	v_add_u32_e32 v4, s1, v22
	ds_write2_b32 v17, v18, v16 offset0:16 offset1:84
	ds_write2_b32 v17, v14, v12 offset0:152 offset1:220
	ds_write2_b32 v9, v10, v8 offset0:32 offset1:100
	ds_write_b32 v185, v6 offset:2720
	v_max_i32_e32 v21, 8, v4
	v_add_u32_e32 v23, 8, v4
	s_mov_b64 s[0:1], 0
